# no accumulator zeroing at GEMM unit starts: first half K-iteration peeled with source-C = 0 (six non-fused GEMM loops), on v20
# speedup vs baseline: 1.0089x; 1.0054x over previous
.LBB0_123:
	s_ashr_i32 s19, s18, 31
	v_readlane_b32 s56, v246, 20
	s_lshl_b64 s[20:21], s[18:19], 19
	v_readlane_b32 s70, v246, 34
	v_readlane_b32 s71, v246, 35
	s_add_u32 s20, s70, s20
	s_addc_u32 s21, s71, s21
	s_and_b64 s[22:23], s[0:1], exec
	s_cselect_b32 s5, s21, s3
	s_cselect_b32 s19, s20, s2
	s_ashr_i32 s17, s16, 31
	s_lshl_b64 s[22:23], s[16:17], 19
	s_add_u32 s22, s15, s22
	s_addc_u32 s23, s30, s23
	s_and_b64 s[28:29], s[0:1], exec
	s_cselect_b32 s17, s23, s27
	s_cselect_b32 s25, s22, s26
	s_add_u32 s2, s2, 0x40080
	s_addc_u32 s3, s3, 0
	s_add_u32 s33, s26, 0x100
	s_addc_u32 s46, s27, 0
	s_mov_b32 s47, -2
	v_readlane_b32 s57, v246, 21
	v_readlane_b32 s58, v246, 22
	v_readlane_b32 s59, v246, 23
	v_readlane_b32 s60, v246, 24
	v_readlane_b32 s61, v246, 25
	v_readlane_b32 s62, v246, 26
	v_readlane_b32 s63, v246, 27
	v_readlane_b32 s64, v246, 28
	v_readlane_b32 s65, v246, 29
	v_readlane_b32 s66, v246, 30
	v_readlane_b32 s67, v246, 31
	v_readlane_b32 s68, v246, 32
	v_readlane_b32 s69, v246, 33
	ds_read_b128 v[128:131], v161
	ds_read_b128 v[132:135], v161 offset:1024
	ds_read_b128 v[152:155], v161 offset:2048
	ds_read_b128 v[164:167], v161 offset:3072
	ds_read_b128 v[172:175], v162
	ds_read_b128 v[176:179], v162 offset:1024
	ds_read_b128 v[180:183], v162 offset:2048
	ds_read_b128 v[184:187], v162 offset:3072
	s_add_u32 s26, s2, 0xfffc0080
	s_addc_u32 s27, s3, -1
	s_cmp_eq_u32 s47, 12
	s_cselect_b32 s29, s5, s27
	s_cselect_b32 s28, s19, s26
	s_cselect_b32 s27, s17, s46
	s_cselect_b32 s26, s25, s33
	v_lshl_add_u64 v[156:157], s[2:3], 0, v[144:145]
	s_add_i32 m0, s34, 0xc000
	ds_read_b128 v[188:191], v163
	ds_read_b128 v[192:195], v163 offset:1024
	ds_read_b128 v[196:199], v163 offset:2048
	ds_read_b128 v[200:203], v163 offset:3072
	ds_read_b128 v[204:207], v163 offset:4096
	ds_read_b128 v[208:211], v163 offset:5120
	ds_read_b128 v[212:215], v163 offset:6144
	ds_read_b128 v[216:219], v163 offset:7168
	global_load_lds_dwordx4 v[156:157], off
	v_lshl_add_u64 v[156:157], s[2:3], 0, v[146:147]
	s_add_i32 m0, s34, 0xe000
	s_nop 0
	global_load_lds_dwordx4 v[156:157], off
	s_waitcnt vmcnt(8)
	s_waitcnt lgkmcnt(0)
	s_barrier
	s_waitcnt lgkmcnt(0)
	v_mfma_f32_16x16x32_bf16 v[124:127], v[128:131], v[188:191], 0
	v_mfma_f32_16x16x32_bf16 v[120:123], v[152:155], v[188:191], 0
	v_mfma_f32_16x16x32_bf16 v[108:111], v[128:131], v[196:199], 0
	v_mfma_f32_16x16x32_bf16 v[104:107], v[152:155], v[196:199], 0
	v_mfma_f32_16x16x32_bf16 v[92:95], v[128:131], v[204:207], 0
	v_mfma_f32_16x16x32_bf16 v[88:91], v[152:155], v[204:207], 0
	v_mfma_f32_16x16x32_bf16 v[76:79], v[128:131], v[212:215], 0
	v_mfma_f32_16x16x32_bf16 v[72:75], v[152:155], v[212:215], 0
	v_mfma_f32_16x16x32_bf16 v[124:127], v[132:135], v[192:195], v[124:127]
	v_mfma_f32_16x16x32_bf16 v[120:123], v[164:167], v[192:195], v[120:123]
	v_mfma_f32_16x16x32_bf16 v[108:111], v[132:135], v[200:203], v[108:111]
	v_mfma_f32_16x16x32_bf16 v[104:107], v[164:167], v[200:203], v[104:107]
	v_mfma_f32_16x16x32_bf16 v[92:95], v[132:135], v[208:211], v[92:95]
	v_mfma_f32_16x16x32_bf16 v[88:91], v[164:167], v[208:211], v[88:91]
	v_mfma_f32_16x16x32_bf16 v[76:79], v[132:135], v[216:219], v[76:79]
	v_mfma_f32_16x16x32_bf16 v[72:75], v[164:167], v[216:219], v[72:75]
	v_mfma_f32_16x16x32_bf16 v[116:119], v[172:175], v[188:191], 0
	v_mfma_f32_16x16x32_bf16 v[112:115], v[180:183], v[188:191], 0
	v_mfma_f32_16x16x32_bf16 v[100:103], v[172:175], v[196:199], 0
	v_mfma_f32_16x16x32_bf16 v[96:99], v[180:183], v[196:199], 0
	v_mfma_f32_16x16x32_bf16 v[84:87], v[172:175], v[204:207], 0
	v_mfma_f32_16x16x32_bf16 v[80:83], v[180:183], v[204:207], 0
	v_mfma_f32_16x16x32_bf16 v[68:71], v[172:175], v[212:215], 0
	v_mfma_f32_16x16x32_bf16 v[64:67], v[180:183], v[212:215], 0
	v_mfma_f32_16x16x32_bf16 v[116:119], v[176:179], v[192:195], v[116:119]
	v_mfma_f32_16x16x32_bf16 v[112:115], v[184:187], v[192:195], v[112:115]
	v_mfma_f32_16x16x32_bf16 v[100:103], v[176:179], v[200:203], v[100:103]
	v_mfma_f32_16x16x32_bf16 v[96:99], v[184:187], v[200:203], v[96:99]
	v_mfma_f32_16x16x32_bf16 v[84:87], v[176:179], v[208:211], v[84:87]
	v_mfma_f32_16x16x32_bf16 v[80:83], v[184:187], v[208:211], v[80:83]
	v_mfma_f32_16x16x32_bf16 v[68:71], v[176:179], v[216:219], v[68:71]
	v_mfma_f32_16x16x32_bf16 v[64:67], v[184:187], v[216:219], v[64:67]
	s_barrier
	s_add_i32 s49, s44, s31
	v_lshl_add_u64 v[156:157], s[26:27], 0, v[138:139]
	s_mov_b32 m0, s49
	ds_read_b128 v[188:191], v163 offset:16384
	ds_read_b128 v[192:195], v163 offset:17408
	ds_read_b128 v[196:199], v163 offset:18432
	ds_read_b128 v[200:203], v163 offset:19456
	ds_read_b128 v[204:207], v163 offset:20480
	ds_read_b128 v[208:211], v163 offset:21504
	ds_read_b128 v[212:215], v163 offset:22528
	ds_read_b128 v[216:219], v163 offset:23552
	global_load_lds_dwordx4 v[156:157], off
	s_add_i32 m0, s49, 0x2000
	s_add_u32 s50, s26, 0x40000
	v_lshl_add_u64 v[168:169], s[26:27], 0, v[142:143]
	s_addc_u32 s51, s27, 0
	s_add_i32 s49, s45, s31
	global_load_lds_dwordx4 v[168:169], off
	v_lshl_add_u64 v[220:221], s[50:51], 0, v[138:139]
	s_mov_b32 m0, s49
	v_lshl_add_u64 v[222:223], s[28:29], 0, v[140:141]
	global_load_lds_dwordx4 v[220:221], off
	v_lshl_add_u64 v[220:221], s[50:51], 0, v[142:143]
	s_add_i32 m0, s49, 0x2000
	s_nop 0
	global_load_lds_dwordx4 v[220:221], off
	v_lshl_add_u64 v[220:221], s[28:29], 0, v[136:137]
	s_mov_b32 m0, s34
	s_nop 0
	global_load_lds_dwordx4 v[220:221], off
	s_mov_b32 m0, s35
	s_nop 0
	global_load_lds_dwordx4 v[222:223], off
	s_waitcnt vmcnt(8)
	s_waitcnt lgkmcnt(0)
	s_barrier
	s_waitcnt lgkmcnt(0)
	v_mfma_f32_16x16x32_bf16 v[60:63], v[128:131], v[188:191], 0
	v_mfma_f32_16x16x32_bf16 v[56:59], v[152:155], v[188:191], 0
	v_mfma_f32_16x16x32_bf16 v[44:47], v[128:131], v[196:199], 0
	v_mfma_f32_16x16x32_bf16 v[40:43], v[152:155], v[196:199], 0
	v_mfma_f32_16x16x32_bf16 v[28:31], v[128:131], v[204:207], 0
	v_mfma_f32_16x16x32_bf16 v[24:27], v[152:155], v[204:207], 0
	v_mfma_f32_16x16x32_bf16 v[12:15], v[128:131], v[212:215], 0
	v_mfma_f32_16x16x32_bf16 v[8:11], v[152:155], v[212:215], 0
	v_mfma_f32_16x16x32_bf16 v[60:63], v[132:135], v[192:195], v[60:63]
	v_mfma_f32_16x16x32_bf16 v[56:59], v[164:167], v[192:195], v[56:59]
	v_mfma_f32_16x16x32_bf16 v[44:47], v[132:135], v[200:203], v[44:47]
	v_mfma_f32_16x16x32_bf16 v[40:43], v[164:167], v[200:203], v[40:43]
	v_mfma_f32_16x16x32_bf16 v[28:31], v[132:135], v[208:211], v[28:31]
	v_mfma_f32_16x16x32_bf16 v[24:27], v[164:167], v[208:211], v[24:27]
	v_mfma_f32_16x16x32_bf16 v[12:15], v[132:135], v[216:219], v[12:15]
	v_mfma_f32_16x16x32_bf16 v[8:11], v[164:167], v[216:219], v[8:11]
	v_mfma_f32_16x16x32_bf16 v[52:55], v[172:175], v[188:191], 0
	v_mfma_f32_16x16x32_bf16 v[48:51], v[180:183], v[188:191], 0
	v_mfma_f32_16x16x32_bf16 v[36:39], v[172:175], v[196:199], 0
	v_mfma_f32_16x16x32_bf16 v[32:35], v[180:183], v[196:199], 0
	v_mfma_f32_16x16x32_bf16 v[20:23], v[172:175], v[204:207], 0
	v_mfma_f32_16x16x32_bf16 v[16:19], v[180:183], v[204:207], 0
	v_mfma_f32_16x16x32_bf16 v[4:7], v[172:175], v[212:215], 0
	v_mfma_f32_16x16x32_bf16 v[0:3], v[180:183], v[212:215], 0
	v_mfma_f32_16x16x32_bf16 v[52:55], v[176:179], v[192:195], v[52:55]
	v_mfma_f32_16x16x32_bf16 v[48:51], v[184:187], v[192:195], v[48:51]
	v_mfma_f32_16x16x32_bf16 v[36:39], v[176:179], v[200:203], v[36:39]
	v_mfma_f32_16x16x32_bf16 v[32:35], v[184:187], v[200:203], v[32:35]
	v_mfma_f32_16x16x32_bf16 v[20:23], v[176:179], v[208:211], v[20:23]
	v_mfma_f32_16x16x32_bf16 v[16:19], v[184:187], v[208:211], v[16:19]
	v_mfma_f32_16x16x32_bf16 v[4:7], v[176:179], v[216:219], v[4:7]
	v_mfma_f32_16x16x32_bf16 v[0:3], v[184:187], v[216:219], v[0:3]
	s_barrier
	s_branch .Lpeel124_mid

.Lpeel124_mid:
	s_add_i32 s49, 0, 0x18000
	s_add_i32 s50, 0, 0x1c000
	v_add_u32_e32 v164, s49, v159
	v_add_u32_e32 v184, s50, v159
	ds_read_b128 v[128:131], v164
	ds_read_b128 v[132:135], v164 offset:1024
	ds_read_b128 v[152:155], v164 offset:2048
	ds_read_b128 v[164:167], v164 offset:3072
	ds_read_b128 v[172:175], v184
	ds_read_b128 v[176:179], v184 offset:1024
	ds_read_b128 v[180:183], v184 offset:2048
	ds_read_b128 v[184:187], v184 offset:3072
	s_add_u32 s28, s28, 0x40000
	s_addc_u32 s29, s29, 0
	s_mov_b32 m0, s36
	v_lshl_add_u64 v[224:225], s[28:29], 0, v[136:137]
	ds_read_b128 v[188:191], v163 offset:32768
	ds_read_b128 v[192:195], v163 offset:33792
	ds_read_b128 v[196:199], v163 offset:34816
	ds_read_b128 v[200:203], v163 offset:35840
	ds_read_b128 v[204:207], v163 offset:36864
	ds_read_b128 v[208:211], v163 offset:37888
	ds_read_b128 v[212:215], v163 offset:38912
	ds_read_b128 v[216:219], v163 offset:39936
	global_load_lds_dwordx4 v[224:225], off
	v_lshl_add_u64 v[224:225], s[28:29], 0, v[140:141]
	s_mov_b32 m0, s37
	s_nop 0
	global_load_lds_dwordx4 v[224:225], off
	s_waitcnt vmcnt(8)
	s_waitcnt lgkmcnt(0)
	s_barrier
	s_waitcnt lgkmcnt(0)
	v_mfma_f32_16x16x32_bf16 v[124:127], v[128:131], v[188:191], v[124:127]
	v_mfma_f32_16x16x32_bf16 v[120:123], v[152:155], v[188:191], v[120:123]
	v_mfma_f32_16x16x32_bf16 v[108:111], v[128:131], v[196:199], v[108:111]
	v_mfma_f32_16x16x32_bf16 v[104:107], v[152:155], v[196:199], v[104:107]
	v_mfma_f32_16x16x32_bf16 v[92:95], v[128:131], v[204:207], v[92:95]
	v_mfma_f32_16x16x32_bf16 v[88:91], v[152:155], v[204:207], v[88:91]
	v_mfma_f32_16x16x32_bf16 v[76:79], v[128:131], v[212:215], v[76:79]
	v_mfma_f32_16x16x32_bf16 v[72:75], v[152:155], v[212:215], v[72:75]
	v_mfma_f32_16x16x32_bf16 v[124:127], v[132:135], v[192:195], v[124:127]
	v_mfma_f32_16x16x32_bf16 v[120:123], v[164:167], v[192:195], v[120:123]
	v_mfma_f32_16x16x32_bf16 v[108:111], v[132:135], v[200:203], v[108:111]
	v_mfma_f32_16x16x32_bf16 v[104:107], v[164:167], v[200:203], v[104:107]
	v_mfma_f32_16x16x32_bf16 v[92:95], v[132:135], v[208:211], v[92:95]
	v_mfma_f32_16x16x32_bf16 v[88:91], v[164:167], v[208:211], v[88:91]
	v_mfma_f32_16x16x32_bf16 v[76:79], v[132:135], v[216:219], v[76:79]
	v_mfma_f32_16x16x32_bf16 v[72:75], v[164:167], v[216:219], v[72:75]
	v_mfma_f32_16x16x32_bf16 v[116:119], v[172:175], v[188:191], v[116:119]
	v_mfma_f32_16x16x32_bf16 v[112:115], v[180:183], v[188:191], v[112:115]
	v_mfma_f32_16x16x32_bf16 v[100:103], v[172:175], v[196:199], v[100:103]
	v_mfma_f32_16x16x32_bf16 v[96:99], v[180:183], v[196:199], v[96:99]
	v_mfma_f32_16x16x32_bf16 v[84:87], v[172:175], v[204:207], v[84:87]
	v_mfma_f32_16x16x32_bf16 v[80:83], v[180:183], v[204:207], v[80:83]
	v_mfma_f32_16x16x32_bf16 v[68:71], v[172:175], v[212:215], v[68:71]
	v_mfma_f32_16x16x32_bf16 v[64:67], v[180:183], v[212:215], v[64:67]
	v_mfma_f32_16x16x32_bf16 v[116:119], v[176:179], v[192:195], v[116:119]
	v_mfma_f32_16x16x32_bf16 v[112:115], v[184:187], v[192:195], v[112:115]
	v_mfma_f32_16x16x32_bf16 v[100:103], v[176:179], v[200:203], v[100:103]
	v_mfma_f32_16x16x32_bf16 v[96:99], v[184:187], v[200:203], v[96:99]
	v_mfma_f32_16x16x32_bf16 v[84:87], v[176:179], v[208:211], v[84:87]
	v_mfma_f32_16x16x32_bf16 v[80:83], v[184:187], v[208:211], v[80:83]
	v_mfma_f32_16x16x32_bf16 v[68:71], v[176:179], v[216:219], v[68:71]
	v_mfma_f32_16x16x32_bf16 v[64:67], v[184:187], v[216:219], v[64:67]
	s_barrier
	s_add_i32 s28, s49, s31
	v_lshl_add_u64 v[156:157], v[156:157], 0, s[10:11]
	s_mov_b32 m0, s28
	ds_read_b128 v[188:191], v163 offset:49152
	ds_read_b128 v[192:195], v163 offset:50176
	ds_read_b128 v[196:199], v163 offset:51200
	ds_read_b128 v[200:203], v163 offset:52224
	ds_read_b128 v[204:207], v163 offset:53248
	ds_read_b128 v[208:211], v163 offset:54272
	ds_read_b128 v[212:215], v163 offset:55296
	ds_read_b128 v[216:219], v163 offset:56320
	global_load_lds_dwordx4 v[156:157], off
	s_add_i32 m0, s28, 0x2000
	s_add_u32 s26, s26, 0x40080
	v_lshl_add_u64 v[156:157], v[168:169], 0, s[10:11]
	s_addc_u32 s27, s27, 0
	s_add_i32 s28, s50, s31
	global_load_lds_dwordx4 v[156:157], off
	v_lshl_add_u64 v[156:157], s[26:27], 0, v[138:139]
	s_mov_b32 m0, s28
	s_nop 0
	global_load_lds_dwordx4 v[156:157], off
	v_lshl_add_u64 v[156:157], s[26:27], 0, v[142:143]
	s_add_i32 m0, s28, 0x2000
	s_nop 0
	global_load_lds_dwordx4 v[156:157], off
	v_lshl_add_u64 v[156:157], v[220:221], 0, s[10:11]
	s_mov_b32 m0, s41
	s_nop 0
	global_load_lds_dwordx4 v[156:157], off
	v_lshl_add_u64 v[156:157], v[222:223], 0, s[10:11]
	s_mov_b32 m0, s42
	s_nop 0
	global_load_lds_dwordx4 v[156:157], off
	s_waitcnt vmcnt(8)
	s_waitcnt lgkmcnt(0)
	s_barrier
	s_waitcnt lgkmcnt(0)
	v_mfma_f32_16x16x32_bf16 v[60:63], v[128:131], v[188:191], v[60:63]
	v_mfma_f32_16x16x32_bf16 v[56:59], v[152:155], v[188:191], v[56:59]
	v_mfma_f32_16x16x32_bf16 v[44:47], v[128:131], v[196:199], v[44:47]
	v_mfma_f32_16x16x32_bf16 v[40:43], v[152:155], v[196:199], v[40:43]
	v_mfma_f32_16x16x32_bf16 v[28:31], v[128:131], v[204:207], v[28:31]
	v_mfma_f32_16x16x32_bf16 v[24:27], v[152:155], v[204:207], v[24:27]
	v_mfma_f32_16x16x32_bf16 v[12:15], v[128:131], v[212:215], v[12:15]
	v_mfma_f32_16x16x32_bf16 v[8:11], v[152:155], v[212:215], v[8:11]
	v_mfma_f32_16x16x32_bf16 v[60:63], v[132:135], v[192:195], v[60:63]
	v_mfma_f32_16x16x32_bf16 v[56:59], v[164:167], v[192:195], v[56:59]
	v_mfma_f32_16x16x32_bf16 v[44:47], v[132:135], v[200:203], v[44:47]
	v_mfma_f32_16x16x32_bf16 v[40:43], v[164:167], v[200:203], v[40:43]
	v_mfma_f32_16x16x32_bf16 v[28:31], v[132:135], v[208:211], v[28:31]
	v_mfma_f32_16x16x32_bf16 v[24:27], v[164:167], v[208:211], v[24:27]
	v_mfma_f32_16x16x32_bf16 v[12:15], v[132:135], v[216:219], v[12:15]
	v_mfma_f32_16x16x32_bf16 v[8:11], v[164:167], v[216:219], v[8:11]
	v_mfma_f32_16x16x32_bf16 v[52:55], v[172:175], v[188:191], v[52:55]
	v_mfma_f32_16x16x32_bf16 v[48:51], v[180:183], v[188:191], v[48:51]
	v_mfma_f32_16x16x32_bf16 v[36:39], v[172:175], v[196:199], v[36:39]
	v_mfma_f32_16x16x32_bf16 v[32:35], v[180:183], v[196:199], v[32:35]
	v_mfma_f32_16x16x32_bf16 v[20:23], v[172:175], v[204:207], v[20:23]
	v_mfma_f32_16x16x32_bf16 v[16:19], v[180:183], v[204:207], v[16:19]
	v_mfma_f32_16x16x32_bf16 v[4:7], v[172:175], v[212:215], v[4:7]
	v_mfma_f32_16x16x32_bf16 v[0:3], v[180:183], v[212:215], v[0:3]
	v_mfma_f32_16x16x32_bf16 v[52:55], v[176:179], v[192:195], v[52:55]
	v_mfma_f32_16x16x32_bf16 v[48:51], v[184:187], v[192:195], v[48:51]
	v_mfma_f32_16x16x32_bf16 v[36:39], v[176:179], v[200:203], v[36:39]
	v_mfma_f32_16x16x32_bf16 v[32:35], v[184:187], v[200:203], v[32:35]
	v_mfma_f32_16x16x32_bf16 v[20:23], v[176:179], v[208:211], v[20:23]
	v_mfma_f32_16x16x32_bf16 v[16:19], v[184:187], v[208:211], v[16:19]
	v_mfma_f32_16x16x32_bf16 v[4:7], v[176:179], v[216:219], v[4:7]
	v_mfma_f32_16x16x32_bf16 v[0:3], v[184:187], v[216:219], v[0:3]
	s_barrier
	s_add_i32 s47, s47, 2
	s_add_u32 s2, s2, 0x100
	s_addc_u32 s3, s3, 0
	s_add_u32 s33, s33, 0x100
	s_addc_u32 s46, s46, 0
	s_cmp_gt_u32 s47, 13
	s_cbranch_scc0 .LBB0_124
	s_and_b64 vcc, exec, s[12:13]
	s_cbranch_vccz .LBB0_127
	s_barrier

.LBB0_456:
	v_readlane_b32 s56, v246, 20
	v_readlane_b32 s60, v246, 24
	v_readlane_b32 s61, v246, 25
	v_readlane_b32 s62, v246, 26
	v_readlane_b32 s63, v246, 27
	v_readlane_b32 s68, v246, 32
	v_readlane_b32 s69, v246, 33
	s_ashr_i32 s13, s12, 31
	v_readlane_b32 s70, v246, 34
	v_readlane_b32 s71, v246, 35
	s_mov_b64 s[60:61], s[68:69]
	s_lshl_b64 s[14:15], s[12:13], 19
	s_mov_b64 s[62:63], s[70:71]
	s_add_u32 s14, s62, s14
	s_addc_u32 s15, s63, s15
	s_and_b64 s[16:17], s[0:1], exec
	s_cselect_b32 s13, s15, s21
	s_cselect_b32 s42, s14, s20
	s_ashr_i32 s11, s10, 31
	s_lshl_b64 s[16:17], s[10:11], 19
	v_readlane_b32 s24, v246, 36
	v_readlane_b32 s25, v246, 37
	s_add_u32 s16, s24, s16
	s_addc_u32 s17, s25, s17
	s_and_b64 s[24:25], s[0:1], exec
	s_cselect_b32 s11, s17, s23
	s_cselect_b32 s43, s16, s22
	s_add_u32 s20, s20, 0x40080
	s_addc_u32 s21, s21, 0
	s_add_u32 s44, s22, 0x100
	s_addc_u32 s45, s23, 0
	s_mov_b32 s46, -2
	v_readlane_b32 s57, v246, 21
	v_readlane_b32 s58, v246, 22
	v_readlane_b32 s59, v246, 23
	v_readlane_b32 s64, v246, 28
	v_readlane_b32 s65, v246, 29
	v_readlane_b32 s66, v246, 30
	v_readlane_b32 s67, v246, 31
	ds_read_b128 v[152:155], v148
	ds_read_b128 v[156:159], v148 offset:1024
	ds_read_b128 v[160:163], v148 offset:2048
	ds_read_b128 v[164:167], v148 offset:3072
	ds_read_b128 v[172:175], v149
	ds_read_b128 v[176:179], v149 offset:1024
	ds_read_b128 v[180:183], v149 offset:2048
	ds_read_b128 v[184:187], v149 offset:3072
	s_add_u32 s22, s20, 0xfffc0080
	s_addc_u32 s23, s21, -1
	s_cmp_eq_u32 s46, 12
	s_cselect_b32 s25, s13, s23
	s_cselect_b32 s24, s42, s22
	s_cselect_b32 s23, s11, s45
	s_cselect_b32 s22, s43, s44
	v_lshl_add_u64 v[168:169], s[20:21], 0, v[136:137]
	s_add_i32 m0, s19, 0xc000
	ds_read_b128 v[188:191], v150
	ds_read_b128 v[192:195], v150 offset:1024
	ds_read_b128 v[196:199], v150 offset:2048
	ds_read_b128 v[200:203], v150 offset:3072
	ds_read_b128 v[204:207], v150 offset:4096
	ds_read_b128 v[208:211], v150 offset:5120
	ds_read_b128 v[212:215], v150 offset:6144
	ds_read_b128 v[216:219], v150 offset:7168
	global_load_lds_dwordx4 v[168:169], off
	v_lshl_add_u64 v[168:169], s[20:21], 0, v[138:139]
	s_add_i32 m0, s19, 0xe000
	s_nop 0
	global_load_lds_dwordx4 v[168:169], off
	s_waitcnt vmcnt(8)
	s_waitcnt lgkmcnt(0)
	s_barrier
	s_waitcnt lgkmcnt(0)
	v_mfma_f32_16x16x32_bf16 v[124:127], v[152:155], v[188:191], 0
	v_mfma_f32_16x16x32_bf16 v[120:123], v[160:163], v[188:191], 0
	v_mfma_f32_16x16x32_bf16 v[116:119], v[152:155], v[196:199], 0
	v_mfma_f32_16x16x32_bf16 v[108:111], v[160:163], v[196:199], 0
	v_mfma_f32_16x16x32_bf16 v[100:103], v[152:155], v[204:207], 0
	v_mfma_f32_16x16x32_bf16 v[92:95], v[160:163], v[204:207], 0
	v_mfma_f32_16x16x32_bf16 v[84:87], v[152:155], v[212:215], 0
	v_mfma_f32_16x16x32_bf16 v[76:79], v[160:163], v[212:215], 0
	v_mfma_f32_16x16x32_bf16 v[124:127], v[156:159], v[192:195], v[124:127]
	v_mfma_f32_16x16x32_bf16 v[120:123], v[164:167], v[192:195], v[120:123]
	v_mfma_f32_16x16x32_bf16 v[116:119], v[156:159], v[200:203], v[116:119]
	v_mfma_f32_16x16x32_bf16 v[108:111], v[164:167], v[200:203], v[108:111]
	v_mfma_f32_16x16x32_bf16 v[100:103], v[156:159], v[208:211], v[100:103]
	v_mfma_f32_16x16x32_bf16 v[92:95], v[164:167], v[208:211], v[92:95]
	v_mfma_f32_16x16x32_bf16 v[84:87], v[156:159], v[216:219], v[84:87]
	v_mfma_f32_16x16x32_bf16 v[76:79], v[164:167], v[216:219], v[76:79]
	v_mfma_f32_16x16x32_bf16 v[112:115], v[172:175], v[188:191], 0
	v_mfma_f32_16x16x32_bf16 v[104:107], v[180:183], v[188:191], 0
	v_mfma_f32_16x16x32_bf16 v[96:99], v[172:175], v[196:199], 0
	v_mfma_f32_16x16x32_bf16 v[88:91], v[180:183], v[196:199], 0
	v_mfma_f32_16x16x32_bf16 v[80:83], v[172:175], v[204:207], 0
	v_mfma_f32_16x16x32_bf16 v[72:75], v[180:183], v[204:207], 0
	v_mfma_f32_16x16x32_bf16 v[68:71], v[172:175], v[212:215], 0
	v_mfma_f32_16x16x32_bf16 v[64:67], v[180:183], v[212:215], 0
	v_mfma_f32_16x16x32_bf16 v[112:115], v[176:179], v[192:195], v[112:115]
	v_mfma_f32_16x16x32_bf16 v[104:107], v[184:187], v[192:195], v[104:107]
	v_mfma_f32_16x16x32_bf16 v[96:99], v[176:179], v[200:203], v[96:99]
	v_mfma_f32_16x16x32_bf16 v[88:91], v[184:187], v[200:203], v[88:91]
	v_mfma_f32_16x16x32_bf16 v[80:83], v[176:179], v[208:211], v[80:83]
	v_mfma_f32_16x16x32_bf16 v[72:75], v[184:187], v[208:211], v[72:75]
	v_mfma_f32_16x16x32_bf16 v[68:71], v[176:179], v[216:219], v[68:71]
	v_mfma_f32_16x16x32_bf16 v[64:67], v[184:187], v[216:219], v[64:67]
	s_barrier
	s_add_i32 s47, s38, s26
	v_lshl_add_u64 v[168:169], s[22:23], 0, v[130:131]
	s_mov_b32 m0, s47
	ds_read_b128 v[188:191], v150 offset:16384
	ds_read_b128 v[192:195], v150 offset:17408
	ds_read_b128 v[196:199], v150 offset:18432
	ds_read_b128 v[200:203], v150 offset:19456
	ds_read_b128 v[204:207], v150 offset:20480
	ds_read_b128 v[208:211], v150 offset:21504
	ds_read_b128 v[212:215], v150 offset:22528
	ds_read_b128 v[216:219], v150 offset:23552
	global_load_lds_dwordx4 v[168:169], off
	s_add_i32 m0, s47, 0x2000
	s_add_u32 s48, s22, 0x40000
	v_lshl_add_u64 v[220:221], s[22:23], 0, v[134:135]
	s_addc_u32 s49, s23, 0
	s_add_i32 s47, s39, s26
	global_load_lds_dwordx4 v[220:221], off
	v_lshl_add_u64 v[222:223], s[48:49], 0, v[130:131]
	s_mov_b32 m0, s47
	v_lshl_add_u64 v[224:225], s[24:25], 0, v[132:133]
	global_load_lds_dwordx4 v[222:223], off
	v_lshl_add_u64 v[222:223], s[48:49], 0, v[134:135]
	s_add_i32 m0, s47, 0x2000
	s_nop 0
	global_load_lds_dwordx4 v[222:223], off
	v_lshl_add_u64 v[222:223], s[24:25], 0, v[128:129]
	s_mov_b32 m0, s19
	s_nop 0
	global_load_lds_dwordx4 v[222:223], off
	s_mov_b32 m0, s29
	s_nop 0
	global_load_lds_dwordx4 v[224:225], off
	s_waitcnt vmcnt(8)
	s_waitcnt lgkmcnt(0)
	s_barrier
	s_waitcnt lgkmcnt(0)
	v_mfma_f32_16x16x32_bf16 v[60:63], v[152:155], v[188:191], 0
	v_mfma_f32_16x16x32_bf16 v[56:59], v[160:163], v[188:191], 0
	v_mfma_f32_16x16x32_bf16 v[52:55], v[152:155], v[196:199], 0
	v_mfma_f32_16x16x32_bf16 v[44:47], v[160:163], v[196:199], 0
	v_mfma_f32_16x16x32_bf16 v[36:39], v[152:155], v[204:207], 0
	v_mfma_f32_16x16x32_bf16 v[28:31], v[160:163], v[204:207], 0
	v_mfma_f32_16x16x32_bf16 v[20:23], v[152:155], v[212:215], 0
	v_mfma_f32_16x16x32_bf16 v[12:15], v[160:163], v[212:215], 0
	v_mfma_f32_16x16x32_bf16 v[60:63], v[156:159], v[192:195], v[60:63]
	v_mfma_f32_16x16x32_bf16 v[56:59], v[164:167], v[192:195], v[56:59]
	v_mfma_f32_16x16x32_bf16 v[52:55], v[156:159], v[200:203], v[52:55]
	v_mfma_f32_16x16x32_bf16 v[44:47], v[164:167], v[200:203], v[44:47]
	v_mfma_f32_16x16x32_bf16 v[36:39], v[156:159], v[208:211], v[36:39]
	v_mfma_f32_16x16x32_bf16 v[28:31], v[164:167], v[208:211], v[28:31]
	v_mfma_f32_16x16x32_bf16 v[20:23], v[156:159], v[216:219], v[20:23]
	v_mfma_f32_16x16x32_bf16 v[12:15], v[164:167], v[216:219], v[12:15]
	v_mfma_f32_16x16x32_bf16 v[48:51], v[172:175], v[188:191], 0
	v_mfma_f32_16x16x32_bf16 v[40:43], v[180:183], v[188:191], 0
	v_mfma_f32_16x16x32_bf16 v[32:35], v[172:175], v[196:199], 0
	v_mfma_f32_16x16x32_bf16 v[24:27], v[180:183], v[196:199], 0
	v_mfma_f32_16x16x32_bf16 v[16:19], v[172:175], v[204:207], 0
	v_mfma_f32_16x16x32_bf16 v[8:11], v[180:183], v[204:207], 0
	v_mfma_f32_16x16x32_bf16 v[4:7], v[172:175], v[212:215], 0
	v_mfma_f32_16x16x32_bf16 v[0:3], v[180:183], v[212:215], 0
	v_mfma_f32_16x16x32_bf16 v[48:51], v[176:179], v[192:195], v[48:51]
	v_mfma_f32_16x16x32_bf16 v[40:43], v[184:187], v[192:195], v[40:43]
	v_mfma_f32_16x16x32_bf16 v[32:35], v[176:179], v[200:203], v[32:35]
	v_mfma_f32_16x16x32_bf16 v[24:27], v[184:187], v[200:203], v[24:27]
	v_mfma_f32_16x16x32_bf16 v[16:19], v[176:179], v[208:211], v[16:19]
	v_mfma_f32_16x16x32_bf16 v[8:11], v[184:187], v[208:211], v[8:11]
	v_mfma_f32_16x16x32_bf16 v[4:7], v[176:179], v[216:219], v[4:7]
	v_mfma_f32_16x16x32_bf16 v[0:3], v[184:187], v[216:219], v[0:3]
	s_barrier
	s_branch .Lpeel457_mid

.Lpeel457_mid:
	s_add_i32 s47, 0, 0x18000
	v_add_u32_e32 v144, s47, v146
	s_add_i32 s48, 0, 0x1c000
	ds_read_b128 v[152:155], v144
	ds_read_b128 v[156:159], v144 offset:1024
	ds_read_b128 v[160:163], v144 offset:2048
	ds_read_b128 v[164:167], v144 offset:3072
	v_add_u32_e32 v144, s48, v146
	ds_read_b128 v[172:175], v144
	ds_read_b128 v[176:179], v144 offset:1024
	ds_read_b128 v[180:183], v144 offset:2048
	ds_read_b128 v[184:187], v144 offset:3072
	s_add_u32 s24, s24, 0x40000
	s_addc_u32 s25, s25, 0
	s_mov_b32 m0, s30
	v_lshl_add_u64 v[226:227], s[24:25], 0, v[128:129]
	ds_read_b128 v[188:191], v150 offset:32768
	ds_read_b128 v[192:195], v150 offset:33792
	ds_read_b128 v[196:199], v150 offset:34816
	ds_read_b128 v[200:203], v150 offset:35840
	ds_read_b128 v[204:207], v150 offset:36864
	ds_read_b128 v[208:211], v150 offset:37888
	ds_read_b128 v[212:215], v150 offset:38912
	ds_read_b128 v[216:219], v150 offset:39936
	global_load_lds_dwordx4 v[226:227], off
	v_lshl_add_u64 v[226:227], s[24:25], 0, v[132:133]
	s_mov_b32 m0, s31
	s_nop 0
	global_load_lds_dwordx4 v[226:227], off
	s_waitcnt vmcnt(8)
	s_waitcnt lgkmcnt(0)
	s_barrier
	s_waitcnt lgkmcnt(0)
	v_mfma_f32_16x16x32_bf16 v[124:127], v[152:155], v[188:191], v[124:127]
	v_mfma_f32_16x16x32_bf16 v[120:123], v[160:163], v[188:191], v[120:123]
	v_mfma_f32_16x16x32_bf16 v[116:119], v[152:155], v[196:199], v[116:119]
	v_mfma_f32_16x16x32_bf16 v[108:111], v[160:163], v[196:199], v[108:111]
	v_mfma_f32_16x16x32_bf16 v[100:103], v[152:155], v[204:207], v[100:103]
	v_mfma_f32_16x16x32_bf16 v[92:95], v[160:163], v[204:207], v[92:95]
	v_mfma_f32_16x16x32_bf16 v[84:87], v[152:155], v[212:215], v[84:87]
	v_mfma_f32_16x16x32_bf16 v[76:79], v[160:163], v[212:215], v[76:79]
	v_mfma_f32_16x16x32_bf16 v[124:127], v[156:159], v[192:195], v[124:127]
	v_mfma_f32_16x16x32_bf16 v[120:123], v[164:167], v[192:195], v[120:123]
	v_mfma_f32_16x16x32_bf16 v[116:119], v[156:159], v[200:203], v[116:119]
	v_mfma_f32_16x16x32_bf16 v[108:111], v[164:167], v[200:203], v[108:111]
	v_mfma_f32_16x16x32_bf16 v[100:103], v[156:159], v[208:211], v[100:103]
	v_mfma_f32_16x16x32_bf16 v[92:95], v[164:167], v[208:211], v[92:95]
	v_mfma_f32_16x16x32_bf16 v[84:87], v[156:159], v[216:219], v[84:87]
	v_mfma_f32_16x16x32_bf16 v[76:79], v[164:167], v[216:219], v[76:79]
	v_mfma_f32_16x16x32_bf16 v[112:115], v[172:175], v[188:191], v[112:115]
	v_mfma_f32_16x16x32_bf16 v[104:107], v[180:183], v[188:191], v[104:107]
	v_mfma_f32_16x16x32_bf16 v[96:99], v[172:175], v[196:199], v[96:99]
	v_mfma_f32_16x16x32_bf16 v[88:91], v[180:183], v[196:199], v[88:91]
	v_mfma_f32_16x16x32_bf16 v[80:83], v[172:175], v[204:207], v[80:83]
	v_mfma_f32_16x16x32_bf16 v[72:75], v[180:183], v[204:207], v[72:75]
	v_mfma_f32_16x16x32_bf16 v[68:71], v[172:175], v[212:215], v[68:71]
	v_mfma_f32_16x16x32_bf16 v[64:67], v[180:183], v[212:215], v[64:67]
	v_mfma_f32_16x16x32_bf16 v[112:115], v[176:179], v[192:195], v[112:115]
	v_mfma_f32_16x16x32_bf16 v[104:107], v[184:187], v[192:195], v[104:107]
	v_mfma_f32_16x16x32_bf16 v[96:99], v[176:179], v[200:203], v[96:99]
	v_mfma_f32_16x16x32_bf16 v[88:91], v[184:187], v[200:203], v[88:91]
	v_mfma_f32_16x16x32_bf16 v[80:83], v[176:179], v[208:211], v[80:83]
	v_mfma_f32_16x16x32_bf16 v[72:75], v[184:187], v[208:211], v[72:75]
	v_mfma_f32_16x16x32_bf16 v[68:71], v[176:179], v[216:219], v[68:71]
	v_mfma_f32_16x16x32_bf16 v[64:67], v[184:187], v[216:219], v[64:67]
	s_barrier
	s_add_i32 s24, s47, s26
	v_lshl_add_u64 v[168:169], v[168:169], 0, s[6:7]
	s_mov_b32 m0, s24
	ds_read_b128 v[188:191], v150 offset:49152
	ds_read_b128 v[192:195], v150 offset:50176
	ds_read_b128 v[196:199], v150 offset:51200
	ds_read_b128 v[200:203], v150 offset:52224
	ds_read_b128 v[204:207], v150 offset:53248
	ds_read_b128 v[208:211], v150 offset:54272
	ds_read_b128 v[212:215], v150 offset:55296
	ds_read_b128 v[216:219], v150 offset:56320
	global_load_lds_dwordx4 v[168:169], off
	s_add_i32 m0, s24, 0x2000
	s_add_u32 s22, s22, 0x40080
	v_lshl_add_u64 v[168:169], v[220:221], 0, s[6:7]
	s_addc_u32 s23, s23, 0
	s_add_i32 s24, s48, s26
	global_load_lds_dwordx4 v[168:169], off
	v_lshl_add_u64 v[168:169], s[22:23], 0, v[130:131]
	s_mov_b32 m0, s24
	s_nop 0
	global_load_lds_dwordx4 v[168:169], off
	v_lshl_add_u64 v[168:169], s[22:23], 0, v[134:135]
	s_add_i32 m0, s24, 0x2000
	s_nop 0
	global_load_lds_dwordx4 v[168:169], off
	v_lshl_add_u64 v[168:169], v[222:223], 0, s[6:7]
	s_mov_b32 m0, s35
	s_nop 0
	global_load_lds_dwordx4 v[168:169], off
	v_lshl_add_u64 v[168:169], v[224:225], 0, s[6:7]
	s_mov_b32 m0, s36
	s_nop 0
	global_load_lds_dwordx4 v[168:169], off
	s_waitcnt vmcnt(8)
	s_waitcnt lgkmcnt(0)
	s_barrier
	s_waitcnt lgkmcnt(0)
	v_mfma_f32_16x16x32_bf16 v[60:63], v[152:155], v[188:191], v[60:63]
	v_mfma_f32_16x16x32_bf16 v[56:59], v[160:163], v[188:191], v[56:59]
	v_mfma_f32_16x16x32_bf16 v[52:55], v[152:155], v[196:199], v[52:55]
	v_mfma_f32_16x16x32_bf16 v[44:47], v[160:163], v[196:199], v[44:47]
	v_mfma_f32_16x16x32_bf16 v[36:39], v[152:155], v[204:207], v[36:39]
	v_mfma_f32_16x16x32_bf16 v[28:31], v[160:163], v[204:207], v[28:31]
	v_mfma_f32_16x16x32_bf16 v[20:23], v[152:155], v[212:215], v[20:23]
	v_mfma_f32_16x16x32_bf16 v[12:15], v[160:163], v[212:215], v[12:15]
	v_mfma_f32_16x16x32_bf16 v[60:63], v[156:159], v[192:195], v[60:63]
	v_mfma_f32_16x16x32_bf16 v[56:59], v[164:167], v[192:195], v[56:59]
	v_mfma_f32_16x16x32_bf16 v[52:55], v[156:159], v[200:203], v[52:55]
	v_mfma_f32_16x16x32_bf16 v[44:47], v[164:167], v[200:203], v[44:47]
	v_mfma_f32_16x16x32_bf16 v[36:39], v[156:159], v[208:211], v[36:39]
	v_mfma_f32_16x16x32_bf16 v[28:31], v[164:167], v[208:211], v[28:31]
	v_mfma_f32_16x16x32_bf16 v[20:23], v[156:159], v[216:219], v[20:23]
	v_mfma_f32_16x16x32_bf16 v[12:15], v[164:167], v[216:219], v[12:15]
	v_mfma_f32_16x16x32_bf16 v[48:51], v[172:175], v[188:191], v[48:51]
	v_mfma_f32_16x16x32_bf16 v[40:43], v[180:183], v[188:191], v[40:43]
	v_mfma_f32_16x16x32_bf16 v[32:35], v[172:175], v[196:199], v[32:35]
	v_mfma_f32_16x16x32_bf16 v[24:27], v[180:183], v[196:199], v[24:27]
	v_mfma_f32_16x16x32_bf16 v[16:19], v[172:175], v[204:207], v[16:19]
	v_mfma_f32_16x16x32_bf16 v[8:11], v[180:183], v[204:207], v[8:11]
	v_mfma_f32_16x16x32_bf16 v[4:7], v[172:175], v[212:215], v[4:7]
	v_mfma_f32_16x16x32_bf16 v[0:3], v[180:183], v[212:215], v[0:3]
	v_mfma_f32_16x16x32_bf16 v[48:51], v[176:179], v[192:195], v[48:51]
	v_mfma_f32_16x16x32_bf16 v[40:43], v[184:187], v[192:195], v[40:43]
	v_mfma_f32_16x16x32_bf16 v[32:35], v[176:179], v[200:203], v[32:35]
	v_mfma_f32_16x16x32_bf16 v[24:27], v[184:187], v[200:203], v[24:27]
	v_mfma_f32_16x16x32_bf16 v[16:19], v[176:179], v[208:211], v[16:19]
	v_mfma_f32_16x16x32_bf16 v[8:11], v[184:187], v[208:211], v[8:11]
	v_mfma_f32_16x16x32_bf16 v[4:7], v[176:179], v[216:219], v[4:7]
	v_mfma_f32_16x16x32_bf16 v[0:3], v[184:187], v[216:219], v[0:3]
	s_barrier
	s_add_i32 s46, s46, 2
	s_add_u32 s20, s20, 0x100
	s_addc_u32 s21, s21, 0
	s_add_u32 s44, s44, 0x100
	s_addc_u32 s45, s45, 0
	s_cmp_gt_u32 s46, 13
	s_cbranch_scc0 .LBB0_457
	s_and_b64 vcc, exec, s[8:9]
	s_cbranch_vccz .LBB0_460
	s_barrier

.LBB0_645:
	v_readlane_b32 s52, v246, 20
	v_readlane_b32 s60, v246, 28
	v_readlane_b32 s61, v246, 29
	v_readlane_b32 s62, v246, 30
	v_readlane_b32 s63, v246, 31
	v_readlane_b32 s64, v246, 32
	v_readlane_b32 s65, v246, 33
	s_ashr_i32 s17, s16, 31
	v_readlane_b32 s66, v246, 34
	v_readlane_b32 s67, v246, 35
	s_mov_b64 s[60:61], s[64:65]
	s_andn2_b64 vcc, exec, s[34:35]
	s_lshl_b64 s[20:21], s[16:17], 19
	s_mov_b64 s[62:63], s[66:67]
	s_add_u32 s20, s62, s20
	s_addc_u32 s21, s63, s21
	s_and_b64 s[22:23], s[34:35], exec
	s_cselect_b32 s17, s21, s27
	s_cselect_b32 s50, s20, s26
	s_ashr_i32 s19, s18, 31
	s_lshl_b64 s[22:23], s[18:19], 19
	s_add_u32 s22, s38, s22
	s_addc_u32 s23, s40, s23
	v_cndmask_b32_e64 v0, 0, 1, s[34:35]
	s_and_b64 s[34:35], s[34:35], exec
	s_cselect_b32 s19, s23, s29
	s_cselect_b32 s51, s22, s28
	s_add_u32 s26, s26, 0x40080
	s_addc_u32 s27, s27, 0
	v_cmp_ne_u32_e64 s[0:1], 1, v0
	v_readlane_b32 s53, v246, 21
	v_readlane_b32 s54, v246, 22
	s_add_u32 s52, s28, 0x100
	s_addc_u32 s53, s29, 0
	s_mov_b32 s54, -2
	v_readlane_b32 s55, v246, 23
	v_readlane_b32 s56, v246, 24
	v_readlane_b32 s57, v246, 25
	v_readlane_b32 s58, v246, 26
	v_readlane_b32 s59, v246, 27
	ds_read_b128 v[134:137], v156
	ds_read_b128 v[160:163], v156 offset:1024
	ds_read_b128 v[164:167], v156 offset:2048
	ds_read_b128 v[184:187], v156 offset:3072
	ds_read_b128 v[188:191], v157
	ds_read_b128 v[192:195], v157 offset:1024
	ds_read_b128 v[196:199], v157 offset:2048
	ds_read_b128 v[200:203], v157 offset:3072
	s_add_u32 s28, s26, 0xfffc0080
	s_addc_u32 s29, s27, -1
	s_cmp_eq_u32 s54, 12
	s_cselect_b32 s35, s17, s29
	s_cselect_b32 s34, s50, s28
	s_cselect_b32 s29, s19, s53
	s_cselect_b32 s28, s51, s52
	v_lshl_add_u64 v[138:139], s[26:27], 0, v[128:129]
	s_add_i32 m0, s25, 0xc000
	ds_read_b128 v[204:207], v158
	ds_read_b128 v[208:211], v158 offset:1024
	ds_read_b128 v[212:215], v158 offset:2048
	ds_read_b128 v[216:219], v158 offset:3072
	ds_read_b128 v[220:223], v158 offset:4096
	ds_read_b128 v[224:227], v158 offset:5120
	ds_read_b128 v[228:231], v158 offset:6144
	ds_read_b128 v[232:235], v158 offset:7168
	global_load_lds_dwordx4 v[138:139], off
	v_lshl_add_u64 v[138:139], s[26:27], 0, v[132:133]
	s_add_i32 m0, s25, 0xe000
	s_nop 0
	global_load_lds_dwordx4 v[138:139], off
	s_waitcnt vmcnt(8)
	s_waitcnt lgkmcnt(0)
	s_barrier
	s_waitcnt lgkmcnt(0)
	v_mfma_f32_16x16x32_bf16 v[124:127], v[134:137], v[204:207], 0
	v_mfma_f32_16x16x32_bf16 v[120:123], v[164:167], v[204:207], 0
	v_mfma_f32_16x16x32_bf16 v[108:111], v[134:137], v[212:215], 0
	v_mfma_f32_16x16x32_bf16 v[104:107], v[164:167], v[212:215], 0
	v_mfma_f32_16x16x32_bf16 v[92:95], v[134:137], v[220:223], 0
	v_mfma_f32_16x16x32_bf16 v[88:91], v[164:167], v[220:223], 0
	v_mfma_f32_16x16x32_bf16 v[76:79], v[134:137], v[228:231], 0
	v_mfma_f32_16x16x32_bf16 v[72:75], v[164:167], v[228:231], 0
	v_mfma_f32_16x16x32_bf16 v[124:127], v[160:163], v[208:211], v[124:127]
	v_mfma_f32_16x16x32_bf16 v[120:123], v[184:187], v[208:211], v[120:123]
	v_mfma_f32_16x16x32_bf16 v[108:111], v[160:163], v[216:219], v[108:111]
	v_mfma_f32_16x16x32_bf16 v[104:107], v[184:187], v[216:219], v[104:107]
	v_mfma_f32_16x16x32_bf16 v[92:95], v[160:163], v[224:227], v[92:95]
	v_mfma_f32_16x16x32_bf16 v[88:91], v[184:187], v[224:227], v[88:91]
	v_mfma_f32_16x16x32_bf16 v[76:79], v[160:163], v[232:235], v[76:79]
	v_mfma_f32_16x16x32_bf16 v[72:75], v[184:187], v[232:235], v[72:75]
	v_mfma_f32_16x16x32_bf16 v[116:119], v[188:191], v[204:207], 0
	v_mfma_f32_16x16x32_bf16 v[112:115], v[196:199], v[204:207], 0
	v_mfma_f32_16x16x32_bf16 v[100:103], v[188:191], v[212:215], 0
	v_mfma_f32_16x16x32_bf16 v[96:99], v[196:199], v[212:215], 0
	v_mfma_f32_16x16x32_bf16 v[84:87], v[188:191], v[220:223], 0
	v_mfma_f32_16x16x32_bf16 v[80:83], v[196:199], v[220:223], 0
	v_mfma_f32_16x16x32_bf16 v[68:71], v[188:191], v[228:231], 0
	v_mfma_f32_16x16x32_bf16 v[64:67], v[196:199], v[228:231], 0
	v_mfma_f32_16x16x32_bf16 v[116:119], v[192:195], v[208:211], v[116:119]
	v_mfma_f32_16x16x32_bf16 v[112:115], v[200:203], v[208:211], v[112:115]
	v_mfma_f32_16x16x32_bf16 v[100:103], v[192:195], v[216:219], v[100:103]
	v_mfma_f32_16x16x32_bf16 v[96:99], v[200:203], v[216:219], v[96:99]
	v_mfma_f32_16x16x32_bf16 v[84:87], v[192:195], v[224:227], v[84:87]
	v_mfma_f32_16x16x32_bf16 v[80:83], v[200:203], v[224:227], v[80:83]
	v_mfma_f32_16x16x32_bf16 v[68:71], v[192:195], v[232:235], v[68:71]
	v_mfma_f32_16x16x32_bf16 v[64:67], v[200:203], v[232:235], v[64:67]
	s_barrier
	s_add_i32 s55, s47, s41
	v_lshl_add_u64 v[138:139], s[28:29], 0, v[142:143]
	s_mov_b32 m0, s55
	ds_read_b128 v[204:207], v158 offset:16384
	ds_read_b128 v[208:211], v158 offset:17408
	ds_read_b128 v[212:215], v158 offset:18432
	ds_read_b128 v[216:219], v158 offset:19456
	ds_read_b128 v[220:223], v158 offset:20480
	ds_read_b128 v[224:227], v158 offset:21504
	ds_read_b128 v[228:231], v158 offset:22528
	ds_read_b128 v[232:235], v158 offset:23552
	global_load_lds_dwordx4 v[138:139], off
	s_add_i32 m0, s55, 0x2000
	s_add_u32 s56, s28, 0x40000
	v_lshl_add_u64 v[168:169], s[28:29], 0, v[146:147]
	s_addc_u32 s57, s29, 0
	s_add_i32 s55, s48, s41
	global_load_lds_dwordx4 v[168:169], off
	v_lshl_add_u64 v[236:237], s[56:57], 0, v[142:143]
	s_mov_b32 m0, s55
	v_lshl_add_u64 v[238:239], s[34:35], 0, v[144:145]
	global_load_lds_dwordx4 v[236:237], off
	v_lshl_add_u64 v[236:237], s[56:57], 0, v[146:147]
	s_add_i32 m0, s55, 0x2000
	s_nop 0
	global_load_lds_dwordx4 v[236:237], off
	v_lshl_add_u64 v[236:237], s[34:35], 0, v[140:141]
	s_mov_b32 m0, s25
	s_nop 0
	global_load_lds_dwordx4 v[236:237], off
	s_mov_b32 m0, s42
	s_nop 0
	global_load_lds_dwordx4 v[238:239], off
	s_waitcnt vmcnt(8)
	s_waitcnt lgkmcnt(0)
	s_barrier
	s_waitcnt lgkmcnt(0)
	v_mfma_f32_16x16x32_bf16 v[60:63], v[134:137], v[204:207], 0
	v_mfma_f32_16x16x32_bf16 v[56:59], v[164:167], v[204:207], 0
	v_mfma_f32_16x16x32_bf16 v[44:47], v[134:137], v[212:215], 0
	v_mfma_f32_16x16x32_bf16 v[40:43], v[164:167], v[212:215], 0
	v_mfma_f32_16x16x32_bf16 v[28:31], v[134:137], v[220:223], 0
	v_mfma_f32_16x16x32_bf16 v[24:27], v[164:167], v[220:223], 0
	v_mfma_f32_16x16x32_bf16 v[12:15], v[134:137], v[228:231], 0
	v_mfma_f32_16x16x32_bf16 v[8:11], v[164:167], v[228:231], 0
	v_mfma_f32_16x16x32_bf16 v[60:63], v[160:163], v[208:211], v[60:63]
	v_mfma_f32_16x16x32_bf16 v[56:59], v[184:187], v[208:211], v[56:59]
	v_mfma_f32_16x16x32_bf16 v[44:47], v[160:163], v[216:219], v[44:47]
	v_mfma_f32_16x16x32_bf16 v[40:43], v[184:187], v[216:219], v[40:43]
	v_mfma_f32_16x16x32_bf16 v[28:31], v[160:163], v[224:227], v[28:31]
	v_mfma_f32_16x16x32_bf16 v[24:27], v[184:187], v[224:227], v[24:27]
	v_mfma_f32_16x16x32_bf16 v[12:15], v[160:163], v[232:235], v[12:15]
	v_mfma_f32_16x16x32_bf16 v[8:11], v[184:187], v[232:235], v[8:11]
	v_mfma_f32_16x16x32_bf16 v[52:55], v[188:191], v[204:207], 0
	v_mfma_f32_16x16x32_bf16 v[48:51], v[196:199], v[204:207], 0
	v_mfma_f32_16x16x32_bf16 v[36:39], v[188:191], v[212:215], 0
	v_mfma_f32_16x16x32_bf16 v[32:35], v[196:199], v[212:215], 0
	v_mfma_f32_16x16x32_bf16 v[20:23], v[188:191], v[220:223], 0
	v_mfma_f32_16x16x32_bf16 v[16:19], v[196:199], v[220:223], 0
	v_mfma_f32_16x16x32_bf16 v[4:7], v[188:191], v[228:231], 0
	v_mfma_f32_16x16x32_bf16 v[0:3], v[196:199], v[228:231], 0
	v_mfma_f32_16x16x32_bf16 v[52:55], v[192:195], v[208:211], v[52:55]
	v_mfma_f32_16x16x32_bf16 v[48:51], v[200:203], v[208:211], v[48:51]
	v_mfma_f32_16x16x32_bf16 v[36:39], v[192:195], v[216:219], v[36:39]
	v_mfma_f32_16x16x32_bf16 v[32:35], v[200:203], v[216:219], v[32:35]
	v_mfma_f32_16x16x32_bf16 v[20:23], v[192:195], v[224:227], v[20:23]
	v_mfma_f32_16x16x32_bf16 v[16:19], v[200:203], v[224:227], v[16:19]
	v_mfma_f32_16x16x32_bf16 v[4:7], v[192:195], v[232:235], v[4:7]
	v_mfma_f32_16x16x32_bf16 v[0:3], v[200:203], v[232:235], v[0:3]
	s_barrier
	s_branch .Lpeel646_mid

.Lpeel646_mid:
	s_add_i32 s55, 0, 0x18000
	v_add_u32_e32 v130, s55, v154
	s_add_i32 s56, 0, 0x1c000
	ds_read_b128 v[134:137], v130
	ds_read_b128 v[160:163], v130 offset:1024
	ds_read_b128 v[164:167], v130 offset:2048
	ds_read_b128 v[184:187], v130 offset:3072
	v_add_u32_e32 v130, s56, v154
	ds_read_b128 v[188:191], v130
	ds_read_b128 v[192:195], v130 offset:1024
	ds_read_b128 v[196:199], v130 offset:2048
	ds_read_b128 v[200:203], v130 offset:3072
	s_add_u32 s34, s34, 0x40000
	s_addc_u32 s35, s35, 0
	s_mov_b32 m0, s43
	v_lshl_add_u64 v[240:241], s[34:35], 0, v[140:141]
	ds_read_b128 v[204:207], v158 offset:32768
	ds_read_b128 v[208:211], v158 offset:33792
	ds_read_b128 v[212:215], v158 offset:34816
	ds_read_b128 v[216:219], v158 offset:35840
	ds_read_b128 v[220:223], v158 offset:36864
	ds_read_b128 v[224:227], v158 offset:37888
	ds_read_b128 v[228:231], v158 offset:38912
	ds_read_b128 v[232:235], v158 offset:39936
	global_load_lds_dwordx4 v[240:241], off
	v_lshl_add_u64 v[240:241], s[34:35], 0, v[144:145]
	s_mov_b32 m0, s44
	s_nop 0
	global_load_lds_dwordx4 v[240:241], off
	s_waitcnt vmcnt(8)
	s_waitcnt lgkmcnt(0)
	s_barrier
	s_waitcnt lgkmcnt(0)
	v_mfma_f32_16x16x32_bf16 v[124:127], v[134:137], v[204:207], v[124:127]
	v_mfma_f32_16x16x32_bf16 v[120:123], v[164:167], v[204:207], v[120:123]
	v_mfma_f32_16x16x32_bf16 v[108:111], v[134:137], v[212:215], v[108:111]
	v_mfma_f32_16x16x32_bf16 v[104:107], v[164:167], v[212:215], v[104:107]
	v_mfma_f32_16x16x32_bf16 v[92:95], v[134:137], v[220:223], v[92:95]
	v_mfma_f32_16x16x32_bf16 v[88:91], v[164:167], v[220:223], v[88:91]
	v_mfma_f32_16x16x32_bf16 v[76:79], v[134:137], v[228:231], v[76:79]
	v_mfma_f32_16x16x32_bf16 v[72:75], v[164:167], v[228:231], v[72:75]
	v_mfma_f32_16x16x32_bf16 v[124:127], v[160:163], v[208:211], v[124:127]
	v_mfma_f32_16x16x32_bf16 v[120:123], v[184:187], v[208:211], v[120:123]
	v_mfma_f32_16x16x32_bf16 v[108:111], v[160:163], v[216:219], v[108:111]
	v_mfma_f32_16x16x32_bf16 v[104:107], v[184:187], v[216:219], v[104:107]
	v_mfma_f32_16x16x32_bf16 v[92:95], v[160:163], v[224:227], v[92:95]
	v_mfma_f32_16x16x32_bf16 v[88:91], v[184:187], v[224:227], v[88:91]
	v_mfma_f32_16x16x32_bf16 v[76:79], v[160:163], v[232:235], v[76:79]
	v_mfma_f32_16x16x32_bf16 v[72:75], v[184:187], v[232:235], v[72:75]
	v_mfma_f32_16x16x32_bf16 v[116:119], v[188:191], v[204:207], v[116:119]
	v_mfma_f32_16x16x32_bf16 v[112:115], v[196:199], v[204:207], v[112:115]
	v_mfma_f32_16x16x32_bf16 v[100:103], v[188:191], v[212:215], v[100:103]
	v_mfma_f32_16x16x32_bf16 v[96:99], v[196:199], v[212:215], v[96:99]
	v_mfma_f32_16x16x32_bf16 v[84:87], v[188:191], v[220:223], v[84:87]
	v_mfma_f32_16x16x32_bf16 v[80:83], v[196:199], v[220:223], v[80:83]
	v_mfma_f32_16x16x32_bf16 v[68:71], v[188:191], v[228:231], v[68:71]
	v_mfma_f32_16x16x32_bf16 v[64:67], v[196:199], v[228:231], v[64:67]
	v_mfma_f32_16x16x32_bf16 v[116:119], v[192:195], v[208:211], v[116:119]
	v_mfma_f32_16x16x32_bf16 v[112:115], v[200:203], v[208:211], v[112:115]
	v_mfma_f32_16x16x32_bf16 v[100:103], v[192:195], v[216:219], v[100:103]
	v_mfma_f32_16x16x32_bf16 v[96:99], v[200:203], v[216:219], v[96:99]
	v_mfma_f32_16x16x32_bf16 v[84:87], v[192:195], v[224:227], v[84:87]
	v_mfma_f32_16x16x32_bf16 v[80:83], v[200:203], v[224:227], v[80:83]
	v_mfma_f32_16x16x32_bf16 v[68:71], v[192:195], v[232:235], v[68:71]
	v_mfma_f32_16x16x32_bf16 v[64:67], v[200:203], v[232:235], v[64:67]
	s_barrier
	s_add_i32 s34, s55, s41
	v_lshl_add_u64 v[138:139], v[138:139], 0, s[12:13]
	s_mov_b32 m0, s34
	ds_read_b128 v[204:207], v158 offset:49152
	ds_read_b128 v[208:211], v158 offset:50176
	ds_read_b128 v[212:215], v158 offset:51200
	ds_read_b128 v[216:219], v158 offset:52224
	ds_read_b128 v[220:223], v158 offset:53248
	ds_read_b128 v[224:227], v158 offset:54272
	ds_read_b128 v[228:231], v158 offset:55296
	ds_read_b128 v[232:235], v158 offset:56320
	global_load_lds_dwordx4 v[138:139], off
	s_add_i32 m0, s34, 0x2000
	s_add_u32 s28, s28, 0x40080
	v_lshl_add_u64 v[138:139], v[168:169], 0, s[12:13]
	s_addc_u32 s29, s29, 0
	s_add_i32 s34, s56, s41
	global_load_lds_dwordx4 v[138:139], off
	v_lshl_add_u64 v[138:139], s[28:29], 0, v[142:143]
	s_mov_b32 m0, s34
	s_nop 0
	global_load_lds_dwordx4 v[138:139], off
	v_lshl_add_u64 v[138:139], s[28:29], 0, v[146:147]
	s_add_i32 m0, s34, 0x2000
	s_nop 0
	global_load_lds_dwordx4 v[138:139], off
	v_lshl_add_u64 v[138:139], v[236:237], 0, s[12:13]
	s_mov_b32 m0, s45
	s_nop 0
	global_load_lds_dwordx4 v[138:139], off
	v_lshl_add_u64 v[138:139], v[238:239], 0, s[12:13]
	s_mov_b32 m0, s46
	s_nop 0
	global_load_lds_dwordx4 v[138:139], off
	s_waitcnt vmcnt(8)
	s_waitcnt lgkmcnt(0)
	s_barrier
	s_waitcnt lgkmcnt(0)
	v_mfma_f32_16x16x32_bf16 v[60:63], v[134:137], v[204:207], v[60:63]
	v_mfma_f32_16x16x32_bf16 v[56:59], v[164:167], v[204:207], v[56:59]
	v_mfma_f32_16x16x32_bf16 v[44:47], v[134:137], v[212:215], v[44:47]
	v_mfma_f32_16x16x32_bf16 v[40:43], v[164:167], v[212:215], v[40:43]
	v_mfma_f32_16x16x32_bf16 v[28:31], v[134:137], v[220:223], v[28:31]
	v_mfma_f32_16x16x32_bf16 v[24:27], v[164:167], v[220:223], v[24:27]
	v_mfma_f32_16x16x32_bf16 v[12:15], v[134:137], v[228:231], v[12:15]
	v_mfma_f32_16x16x32_bf16 v[8:11], v[164:167], v[228:231], v[8:11]
	v_mfma_f32_16x16x32_bf16 v[60:63], v[160:163], v[208:211], v[60:63]
	v_mfma_f32_16x16x32_bf16 v[56:59], v[184:187], v[208:211], v[56:59]
	v_mfma_f32_16x16x32_bf16 v[44:47], v[160:163], v[216:219], v[44:47]
	v_mfma_f32_16x16x32_bf16 v[40:43], v[184:187], v[216:219], v[40:43]
	v_mfma_f32_16x16x32_bf16 v[28:31], v[160:163], v[224:227], v[28:31]
	v_mfma_f32_16x16x32_bf16 v[24:27], v[184:187], v[224:227], v[24:27]
	v_mfma_f32_16x16x32_bf16 v[12:15], v[160:163], v[232:235], v[12:15]
	v_mfma_f32_16x16x32_bf16 v[8:11], v[184:187], v[232:235], v[8:11]
	v_mfma_f32_16x16x32_bf16 v[52:55], v[188:191], v[204:207], v[52:55]
	v_mfma_f32_16x16x32_bf16 v[48:51], v[196:199], v[204:207], v[48:51]
	v_mfma_f32_16x16x32_bf16 v[36:39], v[188:191], v[212:215], v[36:39]
	v_mfma_f32_16x16x32_bf16 v[32:35], v[196:199], v[212:215], v[32:35]
	v_mfma_f32_16x16x32_bf16 v[20:23], v[188:191], v[220:223], v[20:23]
	v_mfma_f32_16x16x32_bf16 v[16:19], v[196:199], v[220:223], v[16:19]
	v_mfma_f32_16x16x32_bf16 v[4:7], v[188:191], v[228:231], v[4:7]
	v_mfma_f32_16x16x32_bf16 v[0:3], v[196:199], v[228:231], v[0:3]
	v_mfma_f32_16x16x32_bf16 v[52:55], v[192:195], v[208:211], v[52:55]
	v_mfma_f32_16x16x32_bf16 v[48:51], v[200:203], v[208:211], v[48:51]
	v_mfma_f32_16x16x32_bf16 v[36:39], v[192:195], v[216:219], v[36:39]
	v_mfma_f32_16x16x32_bf16 v[32:35], v[200:203], v[216:219], v[32:35]
	v_mfma_f32_16x16x32_bf16 v[20:23], v[192:195], v[224:227], v[20:23]
	v_mfma_f32_16x16x32_bf16 v[16:19], v[200:203], v[224:227], v[16:19]
	v_mfma_f32_16x16x32_bf16 v[4:7], v[192:195], v[232:235], v[4:7]
	v_mfma_f32_16x16x32_bf16 v[0:3], v[200:203], v[232:235], v[0:3]
	s_barrier
	s_add_i32 s54, s54, 2
	s_add_u32 s26, s26, 0x100
	s_addc_u32 s27, s27, 0
	s_add_u32 s52, s52, 0x100
	s_addc_u32 s53, s53, 0
	s_cmp_gt_u32 s54, 13
	s_cbranch_scc0 .LBB0_646
	s_and_b64 vcc, exec, s[14:15]
	s_cbranch_vccz .LBB0_649
	s_barrier

.LBB0_665:
	s_ashr_i32 s19, s18, 31
	s_lshl_b64 s[20:21], s[18:19], 18
	s_add_u32 s20, s30, s20
	s_addc_u32 s21, s31, s21
	s_and_b64 s[22:23], s[2:3], exec
	s_cselect_b32 s19, s21, s27
	s_cselect_b32 s50, s20, s26
	s_ashr_i32 s17, s16, 31
	s_lshl_b64 s[22:23], s[16:17], 18
	v_readlane_b32 s34, v246, 38
	v_readlane_b32 s35, v246, 39
	s_add_u32 s22, s34, s22
	s_addc_u32 s23, s35, s23
	s_and_b64 s[34:35], s[2:3], exec
	s_cselect_b32 s17, s23, s29
	s_cselect_b32 s51, s22, s28
	s_add_u32 s26, s26, 0x20080
	s_addc_u32 s27, s27, 0
	s_add_u32 s52, s28, 0x100
	s_addc_u32 s53, s29, 0
	s_mov_b32 s54, -2
	ds_read_b128 v[128:131], v187
	ds_read_b128 v[132:135], v187 offset:1024
	ds_read_b128 v[136:139], v187 offset:2048
	ds_read_b128 v[164:167], v187 offset:3072
	ds_read_b128 v[190:193], v188
	ds_read_b128 v[194:197], v188 offset:1024
	ds_read_b128 v[198:201], v188 offset:2048
	ds_read_b128 v[202:205], v188 offset:3072
	s_add_u32 s28, s26, 0xfffe0080
	s_addc_u32 s29, s27, -1
	s_cmp_eq_u32 s54, 4
	s_cselect_b32 s35, s19, s29
	s_cselect_b32 s34, s50, s28
	s_cselect_b32 s29, s17, s53
	s_cselect_b32 s28, s51, s52
	v_lshl_add_u64 v[168:169], s[26:27], 0, v[156:157]
	s_add_i32 m0, s25, 0xc000
	ds_read_b128 v[206:209], v189
	ds_read_b128 v[210:213], v189 offset:1024
	ds_read_b128 v[214:217], v189 offset:2048
	ds_read_b128 v[218:221], v189 offset:3072
	ds_read_b128 v[222:225], v189 offset:4096
	ds_read_b128 v[226:229], v189 offset:5120
	ds_read_b128 v[230:233], v189 offset:6144
	ds_read_b128 v[234:237], v189 offset:7168
	global_load_lds_dwordx4 v[168:169], off
	v_lshl_add_u64 v[168:169], s[26:27], 0, v[158:159]
	s_add_i32 m0, s25, 0xe000
	s_nop 0
	global_load_lds_dwordx4 v[168:169], off
	s_waitcnt vmcnt(8)
	s_waitcnt lgkmcnt(0)
	s_barrier
	s_waitcnt lgkmcnt(0)
	v_mfma_f32_16x16x32_bf16 v[124:127], v[128:131], v[206:209], 0
	v_mfma_f32_16x16x32_bf16 v[120:123], v[136:139], v[206:209], 0
	v_mfma_f32_16x16x32_bf16 v[112:115], v[128:131], v[214:217], 0
	v_mfma_f32_16x16x32_bf16 v[104:107], v[136:139], v[214:217], 0
	v_mfma_f32_16x16x32_bf16 v[92:95], v[128:131], v[222:225], 0
	v_mfma_f32_16x16x32_bf16 v[88:91], v[136:139], v[222:225], 0
	v_mfma_f32_16x16x32_bf16 v[76:79], v[128:131], v[230:233], 0
	v_mfma_f32_16x16x32_bf16 v[72:75], v[136:139], v[230:233], 0
	v_mfma_f32_16x16x32_bf16 v[124:127], v[132:135], v[210:213], v[124:127]
	v_mfma_f32_16x16x32_bf16 v[120:123], v[164:167], v[210:213], v[120:123]
	v_mfma_f32_16x16x32_bf16 v[112:115], v[132:135], v[218:221], v[112:115]
	v_mfma_f32_16x16x32_bf16 v[104:107], v[164:167], v[218:221], v[104:107]
	v_mfma_f32_16x16x32_bf16 v[92:95], v[132:135], v[226:229], v[92:95]
	v_mfma_f32_16x16x32_bf16 v[88:91], v[164:167], v[226:229], v[88:91]
	v_mfma_f32_16x16x32_bf16 v[76:79], v[132:135], v[234:237], v[76:79]
	v_mfma_f32_16x16x32_bf16 v[72:75], v[164:167], v[234:237], v[72:75]
	v_mfma_f32_16x16x32_bf16 v[116:119], v[190:193], v[206:209], 0
	v_mfma_f32_16x16x32_bf16 v[108:111], v[198:201], v[206:209], 0
	v_mfma_f32_16x16x32_bf16 v[100:103], v[190:193], v[214:217], 0
	v_mfma_f32_16x16x32_bf16 v[96:99], v[198:201], v[214:217], 0
	v_mfma_f32_16x16x32_bf16 v[84:87], v[190:193], v[222:225], 0
	v_mfma_f32_16x16x32_bf16 v[80:83], v[198:201], v[222:225], 0
	v_mfma_f32_16x16x32_bf16 v[68:71], v[190:193], v[230:233], 0
	v_mfma_f32_16x16x32_bf16 v[64:67], v[198:201], v[230:233], 0
	v_mfma_f32_16x16x32_bf16 v[116:119], v[194:197], v[210:213], v[116:119]
	v_mfma_f32_16x16x32_bf16 v[108:111], v[202:205], v[210:213], v[108:111]
	v_mfma_f32_16x16x32_bf16 v[100:103], v[194:197], v[218:221], v[100:103]
	v_mfma_f32_16x16x32_bf16 v[96:99], v[202:205], v[218:221], v[96:99]
	v_mfma_f32_16x16x32_bf16 v[84:87], v[194:197], v[226:229], v[84:87]
	v_mfma_f32_16x16x32_bf16 v[80:83], v[202:205], v[226:229], v[80:83]
	v_mfma_f32_16x16x32_bf16 v[68:71], v[194:197], v[234:237], v[68:71]
	v_mfma_f32_16x16x32_bf16 v[64:67], v[202:205], v[234:237], v[64:67]
	s_barrier
	s_add_i32 s55, s47, s40
	v_lshl_add_u64 v[168:169], s[28:29], 0, v[150:151]
	s_mov_b32 m0, s55
	ds_read_b128 v[206:209], v189 offset:16384
	ds_read_b128 v[210:213], v189 offset:17408
	ds_read_b128 v[214:217], v189 offset:18432
	ds_read_b128 v[218:221], v189 offset:19456
	ds_read_b128 v[222:225], v189 offset:20480
	ds_read_b128 v[226:229], v189 offset:21504
	ds_read_b128 v[230:233], v189 offset:22528
	ds_read_b128 v[234:237], v189 offset:23552
	global_load_lds_dwordx4 v[168:169], off
	s_add_i32 m0, s55, 0x2000
	s_add_u32 s56, s28, 0x20000
	v_lshl_add_u64 v[238:239], s[28:29], 0, v[154:155]
	s_addc_u32 s57, s29, 0
	s_add_i32 s55, s48, s40
	global_load_lds_dwordx4 v[238:239], off
	v_lshl_add_u64 v[240:241], s[56:57], 0, v[150:151]
	s_mov_b32 m0, s55
	v_lshl_add_u64 v[242:243], s[34:35], 0, v[152:153]
	global_load_lds_dwordx4 v[240:241], off
	v_lshl_add_u64 v[240:241], s[56:57], 0, v[154:155]
	s_add_i32 m0, s55, 0x2000
	s_nop 0
	global_load_lds_dwordx4 v[240:241], off
	v_lshl_add_u64 v[240:241], s[34:35], 0, v[148:149]
	s_mov_b32 m0, s25
	s_nop 0
	global_load_lds_dwordx4 v[240:241], off
	s_mov_b32 m0, s41
	s_nop 0
	global_load_lds_dwordx4 v[242:243], off
	s_waitcnt vmcnt(8)
	s_waitcnt lgkmcnt(0)
	s_barrier
	s_waitcnt lgkmcnt(0)
	v_mfma_f32_16x16x32_bf16 v[60:63], v[128:131], v[206:209], 0
	v_mfma_f32_16x16x32_bf16 v[56:59], v[136:139], v[206:209], 0
	v_mfma_f32_16x16x32_bf16 v[44:47], v[128:131], v[214:217], 0
	v_mfma_f32_16x16x32_bf16 v[40:43], v[136:139], v[214:217], 0
	v_mfma_f32_16x16x32_bf16 v[36:39], v[128:131], v[222:225], 0
	v_mfma_f32_16x16x32_bf16 v[32:35], v[136:139], v[222:225], 0
	v_mfma_f32_16x16x32_bf16 v[20:23], v[128:131], v[230:233], 0
	v_mfma_f32_16x16x32_bf16 v[16:19], v[136:139], v[230:233], 0
	v_mfma_f32_16x16x32_bf16 v[60:63], v[132:135], v[210:213], v[60:63]
	v_mfma_f32_16x16x32_bf16 v[56:59], v[164:167], v[210:213], v[56:59]
	v_mfma_f32_16x16x32_bf16 v[44:47], v[132:135], v[218:221], v[44:47]
	v_mfma_f32_16x16x32_bf16 v[40:43], v[164:167], v[218:221], v[40:43]
	v_mfma_f32_16x16x32_bf16 v[36:39], v[132:135], v[226:229], v[36:39]
	v_mfma_f32_16x16x32_bf16 v[32:35], v[164:167], v[226:229], v[32:35]
	v_mfma_f32_16x16x32_bf16 v[20:23], v[132:135], v[234:237], v[20:23]
	v_mfma_f32_16x16x32_bf16 v[16:19], v[164:167], v[234:237], v[16:19]
	v_mfma_f32_16x16x32_bf16 v[52:55], v[190:193], v[206:209], 0
	v_mfma_f32_16x16x32_bf16 v[48:51], v[198:201], v[206:209], 0
	v_mfma_f32_16x16x32_bf16 v[28:31], v[190:193], v[214:217], 0
	v_mfma_f32_16x16x32_bf16 v[24:27], v[198:201], v[214:217], 0
	v_mfma_f32_16x16x32_bf16 v[12:15], v[190:193], v[222:225], 0
	v_mfma_f32_16x16x32_bf16 v[8:11], v[198:201], v[222:225], 0
	v_mfma_f32_16x16x32_bf16 v[4:7], v[190:193], v[230:233], 0
	v_mfma_f32_16x16x32_bf16 v[0:3], v[198:201], v[230:233], 0
	v_mfma_f32_16x16x32_bf16 v[52:55], v[194:197], v[210:213], v[52:55]
	v_mfma_f32_16x16x32_bf16 v[48:51], v[202:205], v[210:213], v[48:51]
	v_mfma_f32_16x16x32_bf16 v[28:31], v[194:197], v[218:221], v[28:31]
	v_mfma_f32_16x16x32_bf16 v[24:27], v[202:205], v[218:221], v[24:27]
	v_mfma_f32_16x16x32_bf16 v[12:15], v[194:197], v[226:229], v[12:15]
	v_mfma_f32_16x16x32_bf16 v[8:11], v[202:205], v[226:229], v[8:11]
	v_mfma_f32_16x16x32_bf16 v[4:7], v[194:197], v[234:237], v[4:7]
	v_mfma_f32_16x16x32_bf16 v[0:3], v[202:205], v[234:237], v[0:3]
	s_barrier
	s_branch .Lpeel666_mid

.Lpeel666_mid:
	s_add_i32 s55, 0, 0x18000
	s_add_i32 s56, 0, 0x1c000
	v_add_u32_e32 v164, s55, v185
	v_add_u32_e32 v202, s56, v185
	ds_read_b128 v[128:131], v164
	ds_read_b128 v[132:135], v164 offset:1024
	ds_read_b128 v[136:139], v164 offset:2048
	ds_read_b128 v[164:167], v164 offset:3072
	ds_read_b128 v[190:193], v202
	ds_read_b128 v[194:197], v202 offset:1024
	ds_read_b128 v[198:201], v202 offset:2048
	ds_read_b128 v[202:205], v202 offset:3072
	s_add_u32 s34, s34, 0x20000
	s_addc_u32 s35, s35, 0
	s_mov_b32 m0, s42
	v_lshl_add_u64 v[244:245], s[34:35], 0, v[148:149]
	ds_read_b128 v[206:209], v189 offset:32768
	ds_read_b128 v[210:213], v189 offset:33792
	ds_read_b128 v[214:217], v189 offset:34816
	ds_read_b128 v[218:221], v189 offset:35840
	ds_read_b128 v[222:225], v189 offset:36864
	ds_read_b128 v[226:229], v189 offset:37888
	ds_read_b128 v[230:233], v189 offset:38912
	ds_read_b128 v[234:237], v189 offset:39936
	global_load_lds_dwordx4 v[244:245], off
	v_lshl_add_u64 v[244:245], s[34:35], 0, v[152:153]
	s_mov_b32 m0, s43
	s_nop 0
	global_load_lds_dwordx4 v[244:245], off
	s_waitcnt vmcnt(8)
	s_waitcnt lgkmcnt(0)
	s_barrier
	s_waitcnt lgkmcnt(0)
	v_mfma_f32_16x16x32_bf16 v[124:127], v[128:131], v[206:209], v[124:127]
	v_mfma_f32_16x16x32_bf16 v[120:123], v[136:139], v[206:209], v[120:123]
	v_mfma_f32_16x16x32_bf16 v[112:115], v[128:131], v[214:217], v[112:115]
	v_mfma_f32_16x16x32_bf16 v[104:107], v[136:139], v[214:217], v[104:107]
	v_mfma_f32_16x16x32_bf16 v[92:95], v[128:131], v[222:225], v[92:95]
	v_mfma_f32_16x16x32_bf16 v[88:91], v[136:139], v[222:225], v[88:91]
	v_mfma_f32_16x16x32_bf16 v[76:79], v[128:131], v[230:233], v[76:79]
	v_mfma_f32_16x16x32_bf16 v[72:75], v[136:139], v[230:233], v[72:75]
	v_mfma_f32_16x16x32_bf16 v[124:127], v[132:135], v[210:213], v[124:127]
	v_mfma_f32_16x16x32_bf16 v[120:123], v[164:167], v[210:213], v[120:123]
	v_mfma_f32_16x16x32_bf16 v[112:115], v[132:135], v[218:221], v[112:115]
	v_mfma_f32_16x16x32_bf16 v[104:107], v[164:167], v[218:221], v[104:107]
	v_mfma_f32_16x16x32_bf16 v[92:95], v[132:135], v[226:229], v[92:95]
	v_mfma_f32_16x16x32_bf16 v[88:91], v[164:167], v[226:229], v[88:91]
	v_mfma_f32_16x16x32_bf16 v[76:79], v[132:135], v[234:237], v[76:79]
	v_mfma_f32_16x16x32_bf16 v[72:75], v[164:167], v[234:237], v[72:75]
	v_mfma_f32_16x16x32_bf16 v[116:119], v[190:193], v[206:209], v[116:119]
	v_mfma_f32_16x16x32_bf16 v[108:111], v[198:201], v[206:209], v[108:111]
	v_mfma_f32_16x16x32_bf16 v[100:103], v[190:193], v[214:217], v[100:103]
	v_mfma_f32_16x16x32_bf16 v[96:99], v[198:201], v[214:217], v[96:99]
	v_mfma_f32_16x16x32_bf16 v[84:87], v[190:193], v[222:225], v[84:87]
	v_mfma_f32_16x16x32_bf16 v[80:83], v[198:201], v[222:225], v[80:83]
	v_mfma_f32_16x16x32_bf16 v[68:71], v[190:193], v[230:233], v[68:71]
	v_mfma_f32_16x16x32_bf16 v[64:67], v[198:201], v[230:233], v[64:67]
	v_mfma_f32_16x16x32_bf16 v[116:119], v[194:197], v[210:213], v[116:119]
	v_mfma_f32_16x16x32_bf16 v[108:111], v[202:205], v[210:213], v[108:111]
	v_mfma_f32_16x16x32_bf16 v[100:103], v[194:197], v[218:221], v[100:103]
	v_mfma_f32_16x16x32_bf16 v[96:99], v[202:205], v[218:221], v[96:99]
	v_mfma_f32_16x16x32_bf16 v[84:87], v[194:197], v[226:229], v[84:87]
	v_mfma_f32_16x16x32_bf16 v[80:83], v[202:205], v[226:229], v[80:83]
	v_mfma_f32_16x16x32_bf16 v[68:71], v[194:197], v[234:237], v[68:71]
	v_mfma_f32_16x16x32_bf16 v[64:67], v[202:205], v[234:237], v[64:67]
	s_barrier
	s_add_i32 s34, s55, s40
	v_lshl_add_u64 v[168:169], v[168:169], 0, s[12:13]
	s_mov_b32 m0, s34
	ds_read_b128 v[206:209], v189 offset:49152
	ds_read_b128 v[210:213], v189 offset:50176
	ds_read_b128 v[214:217], v189 offset:51200
	ds_read_b128 v[218:221], v189 offset:52224
	ds_read_b128 v[222:225], v189 offset:53248
	ds_read_b128 v[226:229], v189 offset:54272
	ds_read_b128 v[230:233], v189 offset:55296
	ds_read_b128 v[234:237], v189 offset:56320
	global_load_lds_dwordx4 v[168:169], off
	s_add_i32 m0, s34, 0x2000
	s_add_u32 s28, s28, 0x20080
	v_lshl_add_u64 v[168:169], v[238:239], 0, s[12:13]
	s_addc_u32 s29, s29, 0
	s_add_i32 s34, s56, s40
	global_load_lds_dwordx4 v[168:169], off
	v_lshl_add_u64 v[168:169], s[28:29], 0, v[150:151]
	s_mov_b32 m0, s34
	s_nop 0
	global_load_lds_dwordx4 v[168:169], off
	v_lshl_add_u64 v[168:169], s[28:29], 0, v[154:155]
	s_add_i32 m0, s34, 0x2000
	s_nop 0
	global_load_lds_dwordx4 v[168:169], off
	v_lshl_add_u64 v[168:169], v[240:241], 0, s[12:13]
	s_mov_b32 m0, s45
	s_nop 0
	global_load_lds_dwordx4 v[168:169], off
	v_lshl_add_u64 v[168:169], v[242:243], 0, s[12:13]
	s_mov_b32 m0, s46
	s_nop 0
	global_load_lds_dwordx4 v[168:169], off
	s_waitcnt vmcnt(8)
	s_waitcnt lgkmcnt(0)
	s_barrier
	s_waitcnt lgkmcnt(0)
	v_mfma_f32_16x16x32_bf16 v[60:63], v[128:131], v[206:209], v[60:63]
	v_mfma_f32_16x16x32_bf16 v[56:59], v[136:139], v[206:209], v[56:59]
	v_mfma_f32_16x16x32_bf16 v[44:47], v[128:131], v[214:217], v[44:47]
	v_mfma_f32_16x16x32_bf16 v[40:43], v[136:139], v[214:217], v[40:43]
	v_mfma_f32_16x16x32_bf16 v[36:39], v[128:131], v[222:225], v[36:39]
	v_mfma_f32_16x16x32_bf16 v[32:35], v[136:139], v[222:225], v[32:35]
	v_mfma_f32_16x16x32_bf16 v[20:23], v[128:131], v[230:233], v[20:23]
	v_mfma_f32_16x16x32_bf16 v[16:19], v[136:139], v[230:233], v[16:19]
	v_mfma_f32_16x16x32_bf16 v[60:63], v[132:135], v[210:213], v[60:63]
	v_mfma_f32_16x16x32_bf16 v[56:59], v[164:167], v[210:213], v[56:59]
	v_mfma_f32_16x16x32_bf16 v[44:47], v[132:135], v[218:221], v[44:47]
	v_mfma_f32_16x16x32_bf16 v[40:43], v[164:167], v[218:221], v[40:43]
	v_mfma_f32_16x16x32_bf16 v[36:39], v[132:135], v[226:229], v[36:39]
	v_mfma_f32_16x16x32_bf16 v[32:35], v[164:167], v[226:229], v[32:35]
	v_mfma_f32_16x16x32_bf16 v[20:23], v[132:135], v[234:237], v[20:23]
	v_mfma_f32_16x16x32_bf16 v[16:19], v[164:167], v[234:237], v[16:19]
	v_mfma_f32_16x16x32_bf16 v[52:55], v[190:193], v[206:209], v[52:55]
	v_mfma_f32_16x16x32_bf16 v[48:51], v[198:201], v[206:209], v[48:51]
	v_mfma_f32_16x16x32_bf16 v[28:31], v[190:193], v[214:217], v[28:31]
	v_mfma_f32_16x16x32_bf16 v[24:27], v[198:201], v[214:217], v[24:27]
	v_mfma_f32_16x16x32_bf16 v[12:15], v[190:193], v[222:225], v[12:15]
	v_mfma_f32_16x16x32_bf16 v[8:11], v[198:201], v[222:225], v[8:11]
	v_mfma_f32_16x16x32_bf16 v[4:7], v[190:193], v[230:233], v[4:7]
	v_mfma_f32_16x16x32_bf16 v[0:3], v[198:201], v[230:233], v[0:3]
	v_mfma_f32_16x16x32_bf16 v[52:55], v[194:197], v[210:213], v[52:55]
	v_mfma_f32_16x16x32_bf16 v[48:51], v[202:205], v[210:213], v[48:51]
	v_mfma_f32_16x16x32_bf16 v[28:31], v[194:197], v[218:221], v[28:31]
	v_mfma_f32_16x16x32_bf16 v[24:27], v[202:205], v[218:221], v[24:27]
	v_mfma_f32_16x16x32_bf16 v[12:15], v[194:197], v[226:229], v[12:15]
	v_mfma_f32_16x16x32_bf16 v[8:11], v[202:205], v[226:229], v[8:11]
	v_mfma_f32_16x16x32_bf16 v[4:7], v[194:197], v[234:237], v[4:7]
	v_mfma_f32_16x16x32_bf16 v[0:3], v[202:205], v[234:237], v[0:3]
	s_barrier
	s_add_i32 s54, s54, 2
	s_add_u32 s26, s26, 0x100
	s_addc_u32 s27, s27, 0
	s_add_u32 s52, s52, 0x100
	s_addc_u32 s53, s53, 0
	s_cmp_gt_u32 s54, 5
	s_cbranch_scc0 .LBB0_666
	s_and_b64 vcc, exec, s[14:15]
	s_cbranch_vccz .LBB0_669
	s_barrier

.LBB0_685:
	s_ashr_i32 s23, s22, 31
	s_lshl_b64 s[24:25], s[22:23], 19
	s_add_u32 s24, s72, s24
	s_addc_u32 s25, s73, s25
	s_and_b64 s[26:27], s[0:1], exec
	s_cselect_b32 s23, s25, s31
	s_cselect_b32 s49, s24, s30
	s_ashr_i32 s21, s20, 31
	s_lshl_b64 s[26:27], s[20:21], 19
	v_readlane_b32 s36, v246, 40
	v_readlane_b32 s37, v246, 41
	s_add_u32 s26, s36, s26
	s_addc_u32 s27, s37, s27
	s_and_b64 s[36:37], s[0:1], exec
	s_cselect_b32 s21, s27, s35
	s_cselect_b32 s50, s26, s34
	s_add_u32 s30, s30, 0x40080
	s_addc_u32 s31, s31, 0
	s_add_u32 s51, s34, 0x100
	s_addc_u32 s52, s35, 0
	s_mov_b32 s53, -2
	ds_read_b128 v[136:139], v153
	ds_read_b128 v[156:159], v153 offset:1024
	ds_read_b128 v[160:163], v153 offset:2048
	ds_read_b128 v[164:167], v153 offset:3072
	ds_read_b128 v[180:183], v154
	ds_read_b128 v[184:187], v154 offset:1024
	ds_read_b128 v[188:191], v154 offset:2048
	ds_read_b128 v[192:195], v154 offset:3072
	s_add_u32 s34, s30, 0xfffc0080
	s_addc_u32 s35, s31, -1
	s_cmp_eq_u32 s53, 12
	s_cselect_b32 s37, s23, s35
	s_cselect_b32 s36, s49, s34
	s_cselect_b32 s35, s21, s52
	s_cselect_b32 s34, s50, s51
	v_lshl_add_u64 v[148:149], s[30:31], 0, v[128:129]
	s_add_i32 m0, s29, 0xc000
	ds_read_b128 v[196:199], v155
	ds_read_b128 v[200:203], v155 offset:1024
	ds_read_b128 v[204:207], v155 offset:2048
	ds_read_b128 v[208:211], v155 offset:3072
	ds_read_b128 v[212:215], v155 offset:4096
	ds_read_b128 v[216:219], v155 offset:5120
	ds_read_b128 v[220:223], v155 offset:6144
	ds_read_b128 v[224:227], v155 offset:7168
	global_load_lds_dwordx4 v[148:149], off
	v_lshl_add_u64 v[148:149], s[30:31], 0, v[130:131]
	s_add_i32 m0, s29, 0xe000
	s_nop 0
	global_load_lds_dwordx4 v[148:149], off
	s_waitcnt vmcnt(8)
	s_waitcnt lgkmcnt(0)
	s_barrier
	s_waitcnt lgkmcnt(0)
	v_mfma_f32_16x16x32_bf16 v[124:127], v[136:139], v[196:199], 0
	v_mfma_f32_16x16x32_bf16 v[120:123], v[160:163], v[196:199], 0
	v_mfma_f32_16x16x32_bf16 v[108:111], v[136:139], v[204:207], 0
	v_mfma_f32_16x16x32_bf16 v[104:107], v[160:163], v[204:207], 0
	v_mfma_f32_16x16x32_bf16 v[92:95], v[136:139], v[212:215], 0
	v_mfma_f32_16x16x32_bf16 v[88:91], v[160:163], v[212:215], 0
	v_mfma_f32_16x16x32_bf16 v[76:79], v[136:139], v[220:223], 0
	v_mfma_f32_16x16x32_bf16 v[72:75], v[160:163], v[220:223], 0
	v_mfma_f32_16x16x32_bf16 v[124:127], v[156:159], v[200:203], v[124:127]
	v_mfma_f32_16x16x32_bf16 v[120:123], v[164:167], v[200:203], v[120:123]
	v_mfma_f32_16x16x32_bf16 v[108:111], v[156:159], v[208:211], v[108:111]
	v_mfma_f32_16x16x32_bf16 v[104:107], v[164:167], v[208:211], v[104:107]
	v_mfma_f32_16x16x32_bf16 v[92:95], v[156:159], v[216:219], v[92:95]
	v_mfma_f32_16x16x32_bf16 v[88:91], v[164:167], v[216:219], v[88:91]
	v_mfma_f32_16x16x32_bf16 v[76:79], v[156:159], v[224:227], v[76:79]
	v_mfma_f32_16x16x32_bf16 v[72:75], v[164:167], v[224:227], v[72:75]
	v_mfma_f32_16x16x32_bf16 v[116:119], v[180:183], v[196:199], 0
	v_mfma_f32_16x16x32_bf16 v[112:115], v[188:191], v[196:199], 0
	v_mfma_f32_16x16x32_bf16 v[100:103], v[180:183], v[204:207], 0
	v_mfma_f32_16x16x32_bf16 v[96:99], v[188:191], v[204:207], 0
	v_mfma_f32_16x16x32_bf16 v[84:87], v[180:183], v[212:215], 0
	v_mfma_f32_16x16x32_bf16 v[80:83], v[188:191], v[212:215], 0
	v_mfma_f32_16x16x32_bf16 v[68:71], v[180:183], v[220:223], 0
	v_mfma_f32_16x16x32_bf16 v[64:67], v[188:191], v[220:223], 0
	v_mfma_f32_16x16x32_bf16 v[116:119], v[184:187], v[200:203], v[116:119]
	v_mfma_f32_16x16x32_bf16 v[112:115], v[192:195], v[200:203], v[112:115]
	v_mfma_f32_16x16x32_bf16 v[100:103], v[184:187], v[208:211], v[100:103]
	v_mfma_f32_16x16x32_bf16 v[96:99], v[192:195], v[208:211], v[96:99]
	v_mfma_f32_16x16x32_bf16 v[84:87], v[184:187], v[216:219], v[84:87]
	v_mfma_f32_16x16x32_bf16 v[80:83], v[192:195], v[216:219], v[80:83]
	v_mfma_f32_16x16x32_bf16 v[68:71], v[184:187], v[224:227], v[68:71]
	v_mfma_f32_16x16x32_bf16 v[64:67], v[192:195], v[224:227], v[64:67]
	s_barrier
	s_add_i32 s54, s46, s40
	v_lshl_add_u64 v[148:149], s[34:35], 0, v[142:143]
	s_mov_b32 m0, s54
	ds_read_b128 v[196:199], v155 offset:16384
	ds_read_b128 v[200:203], v155 offset:17408
	ds_read_b128 v[204:207], v155 offset:18432
	ds_read_b128 v[208:211], v155 offset:19456
	ds_read_b128 v[212:215], v155 offset:20480
	ds_read_b128 v[216:219], v155 offset:21504
	ds_read_b128 v[220:223], v155 offset:22528
	ds_read_b128 v[224:227], v155 offset:23552
	global_load_lds_dwordx4 v[148:149], off
	s_add_i32 m0, s54, 0x2000
	s_add_u32 s54, s34, 0x40000
	v_lshl_add_u64 v[168:169], s[34:35], 0, v[146:147]
	s_addc_u32 s55, s35, 0
	s_add_i32 s56, s47, s40
	global_load_lds_dwordx4 v[168:169], off
	v_lshl_add_u64 v[228:229], s[54:55], 0, v[142:143]
	s_mov_b32 m0, s56
	v_lshl_add_u64 v[230:231], s[36:37], 0, v[144:145]
	global_load_lds_dwordx4 v[228:229], off
	v_lshl_add_u64 v[228:229], s[54:55], 0, v[146:147]
	s_add_i32 m0, s56, 0x2000
	s_nop 0
	global_load_lds_dwordx4 v[228:229], off
	v_lshl_add_u64 v[228:229], s[36:37], 0, v[140:141]
	s_mov_b32 m0, s29
	s_nop 0
	global_load_lds_dwordx4 v[228:229], off
	s_mov_b32 m0, s39
	s_nop 0
	global_load_lds_dwordx4 v[230:231], off
	s_waitcnt vmcnt(8)
	s_waitcnt lgkmcnt(0)
	s_barrier
	s_waitcnt lgkmcnt(0)
	v_mfma_f32_16x16x32_bf16 v[60:63], v[136:139], v[196:199], 0
	v_mfma_f32_16x16x32_bf16 v[56:59], v[160:163], v[196:199], 0
	v_mfma_f32_16x16x32_bf16 v[44:47], v[136:139], v[204:207], 0
	v_mfma_f32_16x16x32_bf16 v[40:43], v[160:163], v[204:207], 0
	v_mfma_f32_16x16x32_bf16 v[28:31], v[136:139], v[212:215], 0
	v_mfma_f32_16x16x32_bf16 v[24:27], v[160:163], v[212:215], 0
	v_mfma_f32_16x16x32_bf16 v[12:15], v[136:139], v[220:223], 0
	v_mfma_f32_16x16x32_bf16 v[8:11], v[160:163], v[220:223], 0
	v_mfma_f32_16x16x32_bf16 v[60:63], v[156:159], v[200:203], v[60:63]
	v_mfma_f32_16x16x32_bf16 v[56:59], v[164:167], v[200:203], v[56:59]
	v_mfma_f32_16x16x32_bf16 v[44:47], v[156:159], v[208:211], v[44:47]
	v_mfma_f32_16x16x32_bf16 v[40:43], v[164:167], v[208:211], v[40:43]
	v_mfma_f32_16x16x32_bf16 v[28:31], v[156:159], v[216:219], v[28:31]
	v_mfma_f32_16x16x32_bf16 v[24:27], v[164:167], v[216:219], v[24:27]
	v_mfma_f32_16x16x32_bf16 v[12:15], v[156:159], v[224:227], v[12:15]
	v_mfma_f32_16x16x32_bf16 v[8:11], v[164:167], v[224:227], v[8:11]
	v_mfma_f32_16x16x32_bf16 v[52:55], v[180:183], v[196:199], 0
	v_mfma_f32_16x16x32_bf16 v[48:51], v[188:191], v[196:199], 0
	v_mfma_f32_16x16x32_bf16 v[36:39], v[180:183], v[204:207], 0
	v_mfma_f32_16x16x32_bf16 v[32:35], v[188:191], v[204:207], 0
	v_mfma_f32_16x16x32_bf16 v[20:23], v[180:183], v[212:215], 0
	v_mfma_f32_16x16x32_bf16 v[16:19], v[188:191], v[212:215], 0
	v_mfma_f32_16x16x32_bf16 v[4:7], v[180:183], v[220:223], 0
	v_mfma_f32_16x16x32_bf16 v[0:3], v[188:191], v[220:223], 0
	v_mfma_f32_16x16x32_bf16 v[52:55], v[184:187], v[200:203], v[52:55]
	v_mfma_f32_16x16x32_bf16 v[48:51], v[192:195], v[200:203], v[48:51]
	v_mfma_f32_16x16x32_bf16 v[36:39], v[184:187], v[208:211], v[36:39]
	v_mfma_f32_16x16x32_bf16 v[32:35], v[192:195], v[208:211], v[32:35]
	v_mfma_f32_16x16x32_bf16 v[20:23], v[184:187], v[216:219], v[20:23]
	v_mfma_f32_16x16x32_bf16 v[16:19], v[192:195], v[216:219], v[16:19]
	v_mfma_f32_16x16x32_bf16 v[4:7], v[184:187], v[224:227], v[4:7]
	v_mfma_f32_16x16x32_bf16 v[0:3], v[192:195], v[224:227], v[0:3]
	s_barrier
	s_branch .Lpeel686_mid

.Lpeel686_mid:
	s_add_i32 s54, 0, 0x18000
	s_add_i32 s55, 0, 0x1c000
	v_add_u32_e32 v164, s54, v151
	v_add_u32_e32 v179, s55, v151
	ds_read_b128 v[136:139], v164
	ds_read_b128 v[156:159], v164 offset:1024
	ds_read_b128 v[160:163], v164 offset:2048
	ds_read_b128 v[164:167], v164 offset:3072
	ds_read_b128 v[180:183], v179
	ds_read_b128 v[184:187], v179 offset:1024
	ds_read_b128 v[188:191], v179 offset:2048
	ds_read_b128 v[192:195], v179 offset:3072
	s_add_u32 s36, s36, 0x40000
	s_addc_u32 s37, s37, 0
	s_mov_b32 m0, s41
	v_lshl_add_u64 v[232:233], s[36:37], 0, v[140:141]
	ds_read_b128 v[196:199], v155 offset:32768
	ds_read_b128 v[200:203], v155 offset:33792
	ds_read_b128 v[204:207], v155 offset:34816
	ds_read_b128 v[208:211], v155 offset:35840
	ds_read_b128 v[212:215], v155 offset:36864
	ds_read_b128 v[216:219], v155 offset:37888
	ds_read_b128 v[220:223], v155 offset:38912
	ds_read_b128 v[224:227], v155 offset:39936
	global_load_lds_dwordx4 v[232:233], off
	v_lshl_add_u64 v[232:233], s[36:37], 0, v[144:145]
	s_mov_b32 m0, s42
	s_nop 0
	global_load_lds_dwordx4 v[232:233], off
	s_waitcnt vmcnt(8)
	s_waitcnt lgkmcnt(0)
	s_barrier
	s_waitcnt lgkmcnt(0)
	v_mfma_f32_16x16x32_bf16 v[124:127], v[136:139], v[196:199], v[124:127]
	v_mfma_f32_16x16x32_bf16 v[120:123], v[160:163], v[196:199], v[120:123]
	v_mfma_f32_16x16x32_bf16 v[108:111], v[136:139], v[204:207], v[108:111]
	v_mfma_f32_16x16x32_bf16 v[104:107], v[160:163], v[204:207], v[104:107]
	v_mfma_f32_16x16x32_bf16 v[92:95], v[136:139], v[212:215], v[92:95]
	v_mfma_f32_16x16x32_bf16 v[88:91], v[160:163], v[212:215], v[88:91]
	v_mfma_f32_16x16x32_bf16 v[76:79], v[136:139], v[220:223], v[76:79]
	v_mfma_f32_16x16x32_bf16 v[72:75], v[160:163], v[220:223], v[72:75]
	v_mfma_f32_16x16x32_bf16 v[124:127], v[156:159], v[200:203], v[124:127]
	v_mfma_f32_16x16x32_bf16 v[120:123], v[164:167], v[200:203], v[120:123]
	v_mfma_f32_16x16x32_bf16 v[108:111], v[156:159], v[208:211], v[108:111]
	v_mfma_f32_16x16x32_bf16 v[104:107], v[164:167], v[208:211], v[104:107]
	v_mfma_f32_16x16x32_bf16 v[92:95], v[156:159], v[216:219], v[92:95]
	v_mfma_f32_16x16x32_bf16 v[88:91], v[164:167], v[216:219], v[88:91]
	v_mfma_f32_16x16x32_bf16 v[76:79], v[156:159], v[224:227], v[76:79]
	v_mfma_f32_16x16x32_bf16 v[72:75], v[164:167], v[224:227], v[72:75]
	v_mfma_f32_16x16x32_bf16 v[116:119], v[180:183], v[196:199], v[116:119]
	v_mfma_f32_16x16x32_bf16 v[112:115], v[188:191], v[196:199], v[112:115]
	v_mfma_f32_16x16x32_bf16 v[100:103], v[180:183], v[204:207], v[100:103]
	v_mfma_f32_16x16x32_bf16 v[96:99], v[188:191], v[204:207], v[96:99]
	v_mfma_f32_16x16x32_bf16 v[84:87], v[180:183], v[212:215], v[84:87]
	v_mfma_f32_16x16x32_bf16 v[80:83], v[188:191], v[212:215], v[80:83]
	v_mfma_f32_16x16x32_bf16 v[68:71], v[180:183], v[220:223], v[68:71]
	v_mfma_f32_16x16x32_bf16 v[64:67], v[188:191], v[220:223], v[64:67]
	v_mfma_f32_16x16x32_bf16 v[116:119], v[184:187], v[200:203], v[116:119]
	v_mfma_f32_16x16x32_bf16 v[112:115], v[192:195], v[200:203], v[112:115]
	v_mfma_f32_16x16x32_bf16 v[100:103], v[184:187], v[208:211], v[100:103]
	v_mfma_f32_16x16x32_bf16 v[96:99], v[192:195], v[208:211], v[96:99]
	v_mfma_f32_16x16x32_bf16 v[84:87], v[184:187], v[216:219], v[84:87]
	v_mfma_f32_16x16x32_bf16 v[80:83], v[192:195], v[216:219], v[80:83]
	v_mfma_f32_16x16x32_bf16 v[68:71], v[184:187], v[224:227], v[68:71]
	v_mfma_f32_16x16x32_bf16 v[64:67], v[192:195], v[224:227], v[64:67]
	s_barrier
	s_add_i32 s36, s54, s40
	v_lshl_add_u64 v[148:149], v[148:149], 0, s[10:11]
	s_mov_b32 m0, s36
	ds_read_b128 v[196:199], v155 offset:49152
	ds_read_b128 v[200:203], v155 offset:50176
	ds_read_b128 v[204:207], v155 offset:51200
	ds_read_b128 v[208:211], v155 offset:52224
	ds_read_b128 v[212:215], v155 offset:53248
	ds_read_b128 v[216:219], v155 offset:54272
	ds_read_b128 v[220:223], v155 offset:55296
	ds_read_b128 v[224:227], v155 offset:56320
	global_load_lds_dwordx4 v[148:149], off
	s_add_i32 m0, s36, 0x2000
	s_add_u32 s34, s34, 0x40080
	v_lshl_add_u64 v[148:149], v[168:169], 0, s[10:11]
	s_addc_u32 s35, s35, 0
	s_add_i32 s36, s55, s40
	global_load_lds_dwordx4 v[148:149], off
	v_lshl_add_u64 v[148:149], s[34:35], 0, v[142:143]
	s_mov_b32 m0, s36
	s_nop 0
	global_load_lds_dwordx4 v[148:149], off
	v_lshl_add_u64 v[148:149], s[34:35], 0, v[146:147]
	s_add_i32 m0, s36, 0x2000
	s_nop 0
	global_load_lds_dwordx4 v[148:149], off
	v_lshl_add_u64 v[148:149], v[228:229], 0, s[10:11]
	s_mov_b32 m0, s44
	s_nop 0
	global_load_lds_dwordx4 v[148:149], off
	v_lshl_add_u64 v[148:149], v[230:231], 0, s[10:11]
	s_mov_b32 m0, s45
	s_nop 0
	global_load_lds_dwordx4 v[148:149], off
	s_waitcnt vmcnt(8)
	s_waitcnt lgkmcnt(0)
	s_barrier
	s_waitcnt lgkmcnt(0)
	v_mfma_f32_16x16x32_bf16 v[60:63], v[136:139], v[196:199], v[60:63]
	v_mfma_f32_16x16x32_bf16 v[56:59], v[160:163], v[196:199], v[56:59]
	v_mfma_f32_16x16x32_bf16 v[44:47], v[136:139], v[204:207], v[44:47]
	v_mfma_f32_16x16x32_bf16 v[40:43], v[160:163], v[204:207], v[40:43]
	v_mfma_f32_16x16x32_bf16 v[28:31], v[136:139], v[212:215], v[28:31]
	v_mfma_f32_16x16x32_bf16 v[24:27], v[160:163], v[212:215], v[24:27]
	v_mfma_f32_16x16x32_bf16 v[12:15], v[136:139], v[220:223], v[12:15]
	v_mfma_f32_16x16x32_bf16 v[8:11], v[160:163], v[220:223], v[8:11]
	v_mfma_f32_16x16x32_bf16 v[60:63], v[156:159], v[200:203], v[60:63]
	v_mfma_f32_16x16x32_bf16 v[56:59], v[164:167], v[200:203], v[56:59]
	v_mfma_f32_16x16x32_bf16 v[44:47], v[156:159], v[208:211], v[44:47]
	v_mfma_f32_16x16x32_bf16 v[40:43], v[164:167], v[208:211], v[40:43]
	v_mfma_f32_16x16x32_bf16 v[28:31], v[156:159], v[216:219], v[28:31]
	v_mfma_f32_16x16x32_bf16 v[24:27], v[164:167], v[216:219], v[24:27]
	v_mfma_f32_16x16x32_bf16 v[12:15], v[156:159], v[224:227], v[12:15]
	v_mfma_f32_16x16x32_bf16 v[8:11], v[164:167], v[224:227], v[8:11]
	v_mfma_f32_16x16x32_bf16 v[52:55], v[180:183], v[196:199], v[52:55]
	v_mfma_f32_16x16x32_bf16 v[48:51], v[188:191], v[196:199], v[48:51]
	v_mfma_f32_16x16x32_bf16 v[36:39], v[180:183], v[204:207], v[36:39]
	v_mfma_f32_16x16x32_bf16 v[32:35], v[188:191], v[204:207], v[32:35]
	v_mfma_f32_16x16x32_bf16 v[20:23], v[180:183], v[212:215], v[20:23]
	v_mfma_f32_16x16x32_bf16 v[16:19], v[188:191], v[212:215], v[16:19]
	v_mfma_f32_16x16x32_bf16 v[4:7], v[180:183], v[220:223], v[4:7]
	v_mfma_f32_16x16x32_bf16 v[0:3], v[188:191], v[220:223], v[0:3]
	v_mfma_f32_16x16x32_bf16 v[52:55], v[184:187], v[200:203], v[52:55]
	v_mfma_f32_16x16x32_bf16 v[48:51], v[192:195], v[200:203], v[48:51]
	v_mfma_f32_16x16x32_bf16 v[36:39], v[184:187], v[208:211], v[36:39]
	v_mfma_f32_16x16x32_bf16 v[32:35], v[192:195], v[208:211], v[32:35]
	v_mfma_f32_16x16x32_bf16 v[20:23], v[184:187], v[216:219], v[20:23]
	v_mfma_f32_16x16x32_bf16 v[16:19], v[192:195], v[216:219], v[16:19]
	v_mfma_f32_16x16x32_bf16 v[4:7], v[184:187], v[224:227], v[4:7]
	v_mfma_f32_16x16x32_bf16 v[0:3], v[192:195], v[224:227], v[0:3]
	s_barrier
	s_add_i32 s53, s53, 2
	s_add_u32 s30, s30, 0x100
	s_addc_u32 s31, s31, 0
	s_add_u32 s51, s51, 0x100
	s_addc_u32 s52, s52, 0
	s_cmp_gt_u32 s53, 13
	s_cbranch_scc0 .LBB0_686
	s_and_b64 vcc, exec, s[12:13]
	s_cbranch_vccz .LBB0_689
	s_barrier

.LBB0_941:
	v_readlane_b32 s44, v246, 20
	v_readlane_b32 s48, v246, 24
	v_readlane_b32 s49, v246, 25
	v_readlane_b32 s50, v246, 26
	v_readlane_b32 s51, v246, 27
	v_readlane_b32 s56, v246, 32
	v_readlane_b32 s57, v246, 33
	s_ashr_i32 s15, s14, 31
	v_readlane_b32 s58, v246, 34
	v_readlane_b32 s59, v246, 35
	s_mov_b64 s[48:49], s[56:57]
	s_lshl_b64 s[16:17], s[14:15], 19
	s_mov_b64 s[50:51], s[58:59]
	s_add_u32 s16, s50, s16
	s_addc_u32 s17, s51, s17
	s_and_b64 s[18:19], s[0:1], exec
	s_cselect_b32 s15, s17, s23
	s_cselect_b32 s44, s16, s22
	s_ashr_i32 s13, s12, 31
	s_lshl_b64 s[18:19], s[12:13], 19
	v_readlane_b32 s26, v246, 44
	v_readlane_b32 s27, v246, 45
	s_add_u32 s18, s26, s18
	s_addc_u32 s19, s27, s19
	v_readlane_b32 s45, v246, 21
	s_and_b64 s[26:27], s[0:1], exec
	s_cselect_b32 s13, s19, s25
	s_cselect_b32 s45, s18, s24
	s_add_u32 s22, s22, 0x40080
	v_readlane_b32 s46, v246, 22
	s_addc_u32 s23, s23, 0
	v_readlane_b32 s47, v246, 23
	s_add_u32 s46, s24, 0x100
	s_addc_u32 s47, s25, 0
	s_mov_b32 s48, -2
	v_readlane_b32 s52, v246, 28
	v_readlane_b32 s53, v246, 29
	v_readlane_b32 s54, v246, 30
	v_readlane_b32 s55, v246, 31
	ds_read_b128 v[150:153], v147
	ds_read_b128 v[154:157], v147 offset:1024
	ds_read_b128 v[158:161], v147 offset:2048
	ds_read_b128 v[162:165], v147 offset:3072
	ds_read_b128 v[166:169], v148
	ds_read_b128 v[180:183], v148 offset:1024
	ds_read_b128 v[184:187], v148 offset:2048
	ds_read_b128 v[188:191], v148 offset:3072
	s_add_u32 s24, s22, 0xfffc0080
	s_addc_u32 s25, s23, -1
	s_cmp_eq_u32 s48, 12
	s_cselect_b32 s27, s15, s25
	s_cselect_b32 s26, s44, s24
	s_cselect_b32 s25, s13, s47
	s_cselect_b32 s24, s45, s46
	v_lshl_add_u64 v[224:225], s[22:23], 0, v[136:137]
	s_add_i32 m0, s21, 0xc000
	ds_read_b128 v[192:195], v149
	ds_read_b128 v[196:199], v149 offset:1024
	ds_read_b128 v[200:203], v149 offset:2048
	ds_read_b128 v[204:207], v149 offset:3072
	ds_read_b128 v[208:211], v149 offset:4096
	ds_read_b128 v[212:215], v149 offset:5120
	ds_read_b128 v[216:219], v149 offset:6144
	ds_read_b128 v[220:223], v149 offset:7168
	global_load_lds_dwordx4 v[224:225], off
	v_lshl_add_u64 v[224:225], s[22:23], 0, v[138:139]
	s_add_i32 m0, s21, 0xe000
	s_nop 0
	global_load_lds_dwordx4 v[224:225], off
	s_waitcnt vmcnt(8)
	s_waitcnt lgkmcnt(0)
	s_barrier
	s_waitcnt lgkmcnt(0)
	v_mfma_f32_16x16x32_bf16 v[124:127], v[150:153], v[192:195], 0
	v_mfma_f32_16x16x32_bf16 v[120:123], v[158:161], v[192:195], 0
	v_mfma_f32_16x16x32_bf16 v[108:111], v[150:153], v[200:203], 0
	v_mfma_f32_16x16x32_bf16 v[104:107], v[158:161], v[200:203], 0
	v_mfma_f32_16x16x32_bf16 v[92:95], v[150:153], v[208:211], 0
	v_mfma_f32_16x16x32_bf16 v[88:91], v[158:161], v[208:211], 0
	v_mfma_f32_16x16x32_bf16 v[76:79], v[150:153], v[216:219], 0
	v_mfma_f32_16x16x32_bf16 v[72:75], v[158:161], v[216:219], 0
	v_mfma_f32_16x16x32_bf16 v[124:127], v[154:157], v[196:199], v[124:127]
	v_mfma_f32_16x16x32_bf16 v[120:123], v[162:165], v[196:199], v[120:123]
	v_mfma_f32_16x16x32_bf16 v[108:111], v[154:157], v[204:207], v[108:111]
	v_mfma_f32_16x16x32_bf16 v[104:107], v[162:165], v[204:207], v[104:107]
	v_mfma_f32_16x16x32_bf16 v[92:95], v[154:157], v[212:215], v[92:95]
	v_mfma_f32_16x16x32_bf16 v[88:91], v[162:165], v[212:215], v[88:91]
	v_mfma_f32_16x16x32_bf16 v[76:79], v[154:157], v[220:223], v[76:79]
	v_mfma_f32_16x16x32_bf16 v[72:75], v[162:165], v[220:223], v[72:75]
	v_mfma_f32_16x16x32_bf16 v[116:119], v[166:169], v[192:195], 0
	v_mfma_f32_16x16x32_bf16 v[112:115], v[184:187], v[192:195], 0
	v_mfma_f32_16x16x32_bf16 v[100:103], v[166:169], v[200:203], 0
	v_mfma_f32_16x16x32_bf16 v[96:99], v[184:187], v[200:203], 0
	v_mfma_f32_16x16x32_bf16 v[84:87], v[166:169], v[208:211], 0
	v_mfma_f32_16x16x32_bf16 v[80:83], v[184:187], v[208:211], 0
	v_mfma_f32_16x16x32_bf16 v[68:71], v[166:169], v[216:219], 0
	v_mfma_f32_16x16x32_bf16 v[64:67], v[184:187], v[216:219], 0
	v_mfma_f32_16x16x32_bf16 v[116:119], v[180:183], v[196:199], v[116:119]
	v_mfma_f32_16x16x32_bf16 v[112:115], v[188:191], v[196:199], v[112:115]
	v_mfma_f32_16x16x32_bf16 v[100:103], v[180:183], v[204:207], v[100:103]
	v_mfma_f32_16x16x32_bf16 v[96:99], v[188:191], v[204:207], v[96:99]
	v_mfma_f32_16x16x32_bf16 v[84:87], v[180:183], v[212:215], v[84:87]
	v_mfma_f32_16x16x32_bf16 v[80:83], v[188:191], v[212:215], v[80:83]
	v_mfma_f32_16x16x32_bf16 v[68:71], v[180:183], v[220:223], v[68:71]
	v_mfma_f32_16x16x32_bf16 v[64:67], v[188:191], v[220:223], v[64:67]
	s_barrier
	s_add_i32 s49, s40, s28
	v_lshl_add_u64 v[224:225], s[24:25], 0, v[130:131]
	s_mov_b32 m0, s49
	ds_read_b128 v[192:195], v149 offset:16384
	ds_read_b128 v[196:199], v149 offset:17408
	ds_read_b128 v[200:203], v149 offset:18432
	ds_read_b128 v[204:207], v149 offset:19456
	ds_read_b128 v[208:211], v149 offset:20480
	ds_read_b128 v[212:215], v149 offset:21504
	ds_read_b128 v[216:219], v149 offset:22528
	ds_read_b128 v[220:223], v149 offset:23552
	global_load_lds_dwordx4 v[224:225], off
	s_add_i32 m0, s49, 0x2000
	s_add_u32 s50, s24, 0x40000
	v_lshl_add_u64 v[226:227], s[24:25], 0, v[134:135]
	s_addc_u32 s51, s25, 0
	s_add_i32 s49, s41, s28
	global_load_lds_dwordx4 v[226:227], off
	v_lshl_add_u64 v[228:229], s[50:51], 0, v[130:131]
	s_mov_b32 m0, s49
	v_lshl_add_u64 v[230:231], s[26:27], 0, v[132:133]
	global_load_lds_dwordx4 v[228:229], off
	v_lshl_add_u64 v[228:229], s[50:51], 0, v[134:135]
	s_add_i32 m0, s49, 0x2000
	s_nop 0
	global_load_lds_dwordx4 v[228:229], off
	v_lshl_add_u64 v[228:229], s[26:27], 0, v[128:129]
	s_mov_b32 m0, s21
	s_nop 0
	global_load_lds_dwordx4 v[228:229], off
	s_mov_b32 m0, s31
	s_nop 0
	global_load_lds_dwordx4 v[230:231], off
	s_waitcnt vmcnt(8)
	s_waitcnt lgkmcnt(0)
	s_barrier
	s_waitcnt lgkmcnt(0)
	v_mfma_f32_16x16x32_bf16 v[60:63], v[150:153], v[192:195], 0
	v_mfma_f32_16x16x32_bf16 v[56:59], v[158:161], v[192:195], 0
	v_mfma_f32_16x16x32_bf16 v[44:47], v[150:153], v[200:203], 0
	v_mfma_f32_16x16x32_bf16 v[40:43], v[158:161], v[200:203], 0
	v_mfma_f32_16x16x32_bf16 v[28:31], v[150:153], v[208:211], 0
	v_mfma_f32_16x16x32_bf16 v[24:27], v[158:161], v[208:211], 0
	v_mfma_f32_16x16x32_bf16 v[12:15], v[150:153], v[216:219], 0
	v_mfma_f32_16x16x32_bf16 v[8:11], v[158:161], v[216:219], 0
	v_mfma_f32_16x16x32_bf16 v[60:63], v[154:157], v[196:199], v[60:63]
	v_mfma_f32_16x16x32_bf16 v[56:59], v[162:165], v[196:199], v[56:59]
	v_mfma_f32_16x16x32_bf16 v[44:47], v[154:157], v[204:207], v[44:47]
	v_mfma_f32_16x16x32_bf16 v[40:43], v[162:165], v[204:207], v[40:43]
	v_mfma_f32_16x16x32_bf16 v[28:31], v[154:157], v[212:215], v[28:31]
	v_mfma_f32_16x16x32_bf16 v[24:27], v[162:165], v[212:215], v[24:27]
	v_mfma_f32_16x16x32_bf16 v[12:15], v[154:157], v[220:223], v[12:15]
	v_mfma_f32_16x16x32_bf16 v[8:11], v[162:165], v[220:223], v[8:11]
	v_mfma_f32_16x16x32_bf16 v[52:55], v[166:169], v[192:195], 0
	v_mfma_f32_16x16x32_bf16 v[48:51], v[184:187], v[192:195], 0
	v_mfma_f32_16x16x32_bf16 v[36:39], v[166:169], v[200:203], 0
	v_mfma_f32_16x16x32_bf16 v[32:35], v[184:187], v[200:203], 0
	v_mfma_f32_16x16x32_bf16 v[20:23], v[166:169], v[208:211], 0
	v_mfma_f32_16x16x32_bf16 v[16:19], v[184:187], v[208:211], 0
	v_mfma_f32_16x16x32_bf16 v[4:7], v[166:169], v[216:219], 0
	v_mfma_f32_16x16x32_bf16 v[0:3], v[184:187], v[216:219], 0
	v_mfma_f32_16x16x32_bf16 v[52:55], v[180:183], v[196:199], v[52:55]
	v_mfma_f32_16x16x32_bf16 v[48:51], v[188:191], v[196:199], v[48:51]
	v_mfma_f32_16x16x32_bf16 v[36:39], v[180:183], v[204:207], v[36:39]
	v_mfma_f32_16x16x32_bf16 v[32:35], v[188:191], v[204:207], v[32:35]
	v_mfma_f32_16x16x32_bf16 v[20:23], v[180:183], v[212:215], v[20:23]
	v_mfma_f32_16x16x32_bf16 v[16:19], v[188:191], v[212:215], v[16:19]
	v_mfma_f32_16x16x32_bf16 v[4:7], v[180:183], v[220:223], v[4:7]
	v_mfma_f32_16x16x32_bf16 v[0:3], v[188:191], v[220:223], v[0:3]
	s_barrier
	s_branch .Lpeel942_mid

.Lpeel942_mid:
	s_add_i32 s49, 0, 0x18000
	s_add_i32 s50, 0, 0x1c000
	v_add_u32_e32 v162, s49, v145
	v_add_u32_e32 v179, s50, v145
	ds_read_b128 v[150:153], v162
	ds_read_b128 v[154:157], v162 offset:1024
	ds_read_b128 v[158:161], v162 offset:2048
	ds_read_b128 v[162:165], v162 offset:3072
	ds_read_b128 v[166:169], v179
	ds_read_b128 v[180:183], v179 offset:1024
	ds_read_b128 v[184:187], v179 offset:2048
	ds_read_b128 v[188:191], v179 offset:3072
	s_add_u32 s26, s26, 0x40000
	s_addc_u32 s27, s27, 0
	s_mov_b32 m0, s33
	v_lshl_add_u64 v[232:233], s[26:27], 0, v[128:129]
	ds_read_b128 v[192:195], v149 offset:32768
	ds_read_b128 v[196:199], v149 offset:33792
	ds_read_b128 v[200:203], v149 offset:34816
	ds_read_b128 v[204:207], v149 offset:35840
	ds_read_b128 v[208:211], v149 offset:36864
	ds_read_b128 v[212:215], v149 offset:37888
	ds_read_b128 v[216:219], v149 offset:38912
	ds_read_b128 v[220:223], v149 offset:39936
	global_load_lds_dwordx4 v[232:233], off
	v_lshl_add_u64 v[232:233], s[26:27], 0, v[132:133]
	s_mov_b32 m0, s34
	s_nop 0
	global_load_lds_dwordx4 v[232:233], off
	s_waitcnt vmcnt(8)
	s_waitcnt lgkmcnt(0)
	s_barrier
	s_waitcnt lgkmcnt(0)
	v_mfma_f32_16x16x32_bf16 v[124:127], v[150:153], v[192:195], v[124:127]
	v_mfma_f32_16x16x32_bf16 v[120:123], v[158:161], v[192:195], v[120:123]
	v_mfma_f32_16x16x32_bf16 v[108:111], v[150:153], v[200:203], v[108:111]
	v_mfma_f32_16x16x32_bf16 v[104:107], v[158:161], v[200:203], v[104:107]
	v_mfma_f32_16x16x32_bf16 v[92:95], v[150:153], v[208:211], v[92:95]
	v_mfma_f32_16x16x32_bf16 v[88:91], v[158:161], v[208:211], v[88:91]
	v_mfma_f32_16x16x32_bf16 v[76:79], v[150:153], v[216:219], v[76:79]
	v_mfma_f32_16x16x32_bf16 v[72:75], v[158:161], v[216:219], v[72:75]
	v_mfma_f32_16x16x32_bf16 v[124:127], v[154:157], v[196:199], v[124:127]
	v_mfma_f32_16x16x32_bf16 v[120:123], v[162:165], v[196:199], v[120:123]
	v_mfma_f32_16x16x32_bf16 v[108:111], v[154:157], v[204:207], v[108:111]
	v_mfma_f32_16x16x32_bf16 v[104:107], v[162:165], v[204:207], v[104:107]
	v_mfma_f32_16x16x32_bf16 v[92:95], v[154:157], v[212:215], v[92:95]
	v_mfma_f32_16x16x32_bf16 v[88:91], v[162:165], v[212:215], v[88:91]
	v_mfma_f32_16x16x32_bf16 v[76:79], v[154:157], v[220:223], v[76:79]
	v_mfma_f32_16x16x32_bf16 v[72:75], v[162:165], v[220:223], v[72:75]
	v_mfma_f32_16x16x32_bf16 v[116:119], v[166:169], v[192:195], v[116:119]
	v_mfma_f32_16x16x32_bf16 v[112:115], v[184:187], v[192:195], v[112:115]
	v_mfma_f32_16x16x32_bf16 v[100:103], v[166:169], v[200:203], v[100:103]
	v_mfma_f32_16x16x32_bf16 v[96:99], v[184:187], v[200:203], v[96:99]
	v_mfma_f32_16x16x32_bf16 v[84:87], v[166:169], v[208:211], v[84:87]
	v_mfma_f32_16x16x32_bf16 v[80:83], v[184:187], v[208:211], v[80:83]
	v_mfma_f32_16x16x32_bf16 v[68:71], v[166:169], v[216:219], v[68:71]
	v_mfma_f32_16x16x32_bf16 v[64:67], v[184:187], v[216:219], v[64:67]
	v_mfma_f32_16x16x32_bf16 v[116:119], v[180:183], v[196:199], v[116:119]
	v_mfma_f32_16x16x32_bf16 v[112:115], v[188:191], v[196:199], v[112:115]
	v_mfma_f32_16x16x32_bf16 v[100:103], v[180:183], v[204:207], v[100:103]
	v_mfma_f32_16x16x32_bf16 v[96:99], v[188:191], v[204:207], v[96:99]
	v_mfma_f32_16x16x32_bf16 v[84:87], v[180:183], v[212:215], v[84:87]
	v_mfma_f32_16x16x32_bf16 v[80:83], v[188:191], v[212:215], v[80:83]
	v_mfma_f32_16x16x32_bf16 v[68:71], v[180:183], v[220:223], v[68:71]
	v_mfma_f32_16x16x32_bf16 v[64:67], v[188:191], v[220:223], v[64:67]
	s_barrier
	s_add_i32 s26, s49, s28
	v_lshl_add_u64 v[224:225], v[224:225], 0, s[8:9]
	s_mov_b32 m0, s26
	ds_read_b128 v[192:195], v149 offset:49152
	ds_read_b128 v[196:199], v149 offset:50176
	ds_read_b128 v[200:203], v149 offset:51200
	ds_read_b128 v[204:207], v149 offset:52224
	ds_read_b128 v[208:211], v149 offset:53248
	ds_read_b128 v[212:215], v149 offset:54272
	ds_read_b128 v[216:219], v149 offset:55296
	ds_read_b128 v[220:223], v149 offset:56320
	global_load_lds_dwordx4 v[224:225], off
	s_add_i32 m0, s26, 0x2000
	s_add_u32 s24, s24, 0x40080
	v_lshl_add_u64 v[224:225], v[226:227], 0, s[8:9]
	s_addc_u32 s25, s25, 0
	s_add_i32 s26, s50, s28
	global_load_lds_dwordx4 v[224:225], off
	v_lshl_add_u64 v[224:225], s[24:25], 0, v[130:131]
	s_mov_b32 m0, s26
	s_nop 0
	global_load_lds_dwordx4 v[224:225], off
	v_lshl_add_u64 v[224:225], s[24:25], 0, v[134:135]
	s_add_i32 m0, s26, 0x2000
	s_nop 0
	global_load_lds_dwordx4 v[224:225], off
	v_lshl_add_u64 v[224:225], v[228:229], 0, s[8:9]
	s_mov_b32 m0, s37
	s_nop 0
	global_load_lds_dwordx4 v[224:225], off
	v_lshl_add_u64 v[224:225], v[230:231], 0, s[8:9]
	s_mov_b32 m0, s38
	s_nop 0
	global_load_lds_dwordx4 v[224:225], off
	s_waitcnt vmcnt(8)
	s_waitcnt lgkmcnt(0)
	s_barrier
	s_waitcnt lgkmcnt(0)
	v_mfma_f32_16x16x32_bf16 v[60:63], v[150:153], v[192:195], v[60:63]
	v_mfma_f32_16x16x32_bf16 v[56:59], v[158:161], v[192:195], v[56:59]
	v_mfma_f32_16x16x32_bf16 v[44:47], v[150:153], v[200:203], v[44:47]
	v_mfma_f32_16x16x32_bf16 v[40:43], v[158:161], v[200:203], v[40:43]
	v_mfma_f32_16x16x32_bf16 v[28:31], v[150:153], v[208:211], v[28:31]
	v_mfma_f32_16x16x32_bf16 v[24:27], v[158:161], v[208:211], v[24:27]
	v_mfma_f32_16x16x32_bf16 v[12:15], v[150:153], v[216:219], v[12:15]
	v_mfma_f32_16x16x32_bf16 v[8:11], v[158:161], v[216:219], v[8:11]
	v_mfma_f32_16x16x32_bf16 v[60:63], v[154:157], v[196:199], v[60:63]
	v_mfma_f32_16x16x32_bf16 v[56:59], v[162:165], v[196:199], v[56:59]
	v_mfma_f32_16x16x32_bf16 v[44:47], v[154:157], v[204:207], v[44:47]
	v_mfma_f32_16x16x32_bf16 v[40:43], v[162:165], v[204:207], v[40:43]
	v_mfma_f32_16x16x32_bf16 v[28:31], v[154:157], v[212:215], v[28:31]
	v_mfma_f32_16x16x32_bf16 v[24:27], v[162:165], v[212:215], v[24:27]
	v_mfma_f32_16x16x32_bf16 v[12:15], v[154:157], v[220:223], v[12:15]
	v_mfma_f32_16x16x32_bf16 v[8:11], v[162:165], v[220:223], v[8:11]
	v_mfma_f32_16x16x32_bf16 v[52:55], v[166:169], v[192:195], v[52:55]
	v_mfma_f32_16x16x32_bf16 v[48:51], v[184:187], v[192:195], v[48:51]
	v_mfma_f32_16x16x32_bf16 v[36:39], v[166:169], v[200:203], v[36:39]
	v_mfma_f32_16x16x32_bf16 v[32:35], v[184:187], v[200:203], v[32:35]
	v_mfma_f32_16x16x32_bf16 v[20:23], v[166:169], v[208:211], v[20:23]
	v_mfma_f32_16x16x32_bf16 v[16:19], v[184:187], v[208:211], v[16:19]
	v_mfma_f32_16x16x32_bf16 v[4:7], v[166:169], v[216:219], v[4:7]
	v_mfma_f32_16x16x32_bf16 v[0:3], v[184:187], v[216:219], v[0:3]
	v_mfma_f32_16x16x32_bf16 v[52:55], v[180:183], v[196:199], v[52:55]
	v_mfma_f32_16x16x32_bf16 v[48:51], v[188:191], v[196:199], v[48:51]
	v_mfma_f32_16x16x32_bf16 v[36:39], v[180:183], v[204:207], v[36:39]
	v_mfma_f32_16x16x32_bf16 v[32:35], v[188:191], v[204:207], v[32:35]
	v_mfma_f32_16x16x32_bf16 v[20:23], v[180:183], v[212:215], v[20:23]
	v_mfma_f32_16x16x32_bf16 v[16:19], v[188:191], v[212:215], v[16:19]
	v_mfma_f32_16x16x32_bf16 v[4:7], v[180:183], v[220:223], v[4:7]
	v_mfma_f32_16x16x32_bf16 v[0:3], v[188:191], v[220:223], v[0:3]
	s_barrier
	s_add_i32 s48, s48, 2
	s_add_u32 s22, s22, 0x100
	s_addc_u32 s23, s23, 0
	s_add_u32 s46, s46, 0x100
	s_addc_u32 s47, s47, 0
	s_cmp_gt_u32 s48, 13
	s_cbranch_scc0 .LBB0_942
	s_and_b64 vcc, exec, s[10:11]
	s_cbranch_vccz .LBB0_945
	s_barrier
